# EpiKV K path: mid-group write-through stores deferred to the group end (loads no longer retire behind own-group stores)
# baseline (speedup 1.0000x reference)
;     __device__ __forceinline__ void operator()(const f32x4 (&acc)[2][2][4][2], const pg8::Unit& u, int wr, int wc, int fr, int fq) const {
;     ...
;                 if (pn < 2) {
;                     const int head = 4 * pn + wc;
;                     float ssn = 0.f;
; #pragma unroll
;                     for (int bj = 0; bj < 2; ++bj)
; #pragma unroll
;                         for (int e = 0; e < 8; ++e) ssn += v[bj][e] * v[bj][e];
;                     float pe[8]; unpack8(*(const u32x4*)(U + (size_t)row * NU + UPE + 8 * fq), pe);
; #pragma unroll
;                     for (int e = 0; e < 8; ++e) ssn += pe[e] * pe[e];
;                     ssn += __shfl_xor(ssn, 16); ssn += __shfl_xor(ssn, 32);
;                     const float rk = rsqrtf(ssn * (1.f / 96.f) + EPS);
;                     bf16_t* kb = Kf + ((size_t)(b * 8 + head) * SEQ + s) * 96;
.LBB0_135:
	s_or_b32 s28, s2, s92
	s_add_i32 s2, s3, s28
	s_ashr_i32 s3, s2, 31
	s_lshl_b64 s[48:49], s[2:3], 11
	v_pk_mul_f32 v[202:203], v[138:139], v[200:201] op_sel_hi:[1,0]
	v_pk_mul_f32 v[138:139], v[140:141], v[200:201] op_sel_hi:[1,0]
	v_pk_mul_f32 v[134:135], v[134:135], v[200:201] op_sel_hi:[1,0]
	s_andn2_b64 vcc, exec, s[26:27]
	v_pk_mul_f32 v[136:137], v[136:137], v[200:201] op_sel_hi:[1,0]
	s_cbranch_vccnz .LBB0_137
	v_mov_b64_e32 v[140:141], s[70:71]
	v_mad_i64_i32 v[140:141], s[2:3], v198, s85, v[140:141]
	v_lshl_add_u64 v[140:141], v[140:141], 0, v[0:1]
	v_add_co_u32_e32 v140, vcc, 0x1000, v140
	v_pk_mul_f32 v[196:197], v[148:149], v[148:149]
	s_nop 0
	v_addc_co_u32_e32 v141, vcc, 0, v141, vcc
	global_load_dwordx4 v[204:207], v[140:141], off offset:1792
	global_load_dwordx4 v[208:211], v[170:171], off
	global_load_dwordx4 v[212:215], v[170:171], off offset:16
	v_pk_mul_f32 v[140:141], v[146:147], v[146:147]
	v_pk_mul_f32 v[200:201], v[150:151], v[150:151]
	v_add_f32_e32 v140, v140, v141
	v_add_f32_e32 v140, v196, v140
	v_add_f32_e32 v140, v197, v140
	v_add_f32_e32 v140, v200, v140
	v_pk_mul_f32 v[216:217], v[152:153], v[152:153]
	v_add_f32_e32 v140, v201, v140
	v_add_f32_e32 v140, v216, v140
	v_pk_mul_f32 v[218:219], v[202:203], v[202:203]
	v_add_f32_e32 v140, v217, v140
	v_add_f32_e32 v140, v218, v140
	v_pk_mul_f32 v[220:221], v[138:139], v[138:139]
	v_add_f32_e32 v140, v219, v140
	v_add_f32_e32 v140, v220, v140
	v_pk_mul_f32 v[222:223], v[134:135], v[134:135]
	v_add_f32_e32 v140, v221, v140
	v_add_f32_e32 v140, v222, v140
	v_pk_mul_f32 v[224:225], v[136:137], v[136:137]
	v_add_f32_e32 v140, v223, v140
	v_add_f32_e32 v140, v224, v140
	v_and_b32_e32 v226, 64, v247
	v_add_f32_e32 v222, v225, v140
	v_xor_b32_e32 v195, 16, v247
	v_add_u32_e32 v226, 64, v226
	v_cmp_lt_i32_e32 vcc, v195, v226
	s_movk_i32 s26, 0xc0
	s_mov_b32 s58, s62
	v_cndmask_b32_e32 v141, v247, v195, vcc
	v_lshlrev_b32_e32 v195, 2, v141
	s_mov_b32 s59, s63
	v_readlane_b32 s2, v253, 32
	v_readlane_b32 s3, v253, 33
	s_waitcnt vmcnt(0)
	v_lshlrev_b32_e32 v220, 16, v204
	v_and_b32_e32 v221, 0xffff0000, v204
	v_lshlrev_b32_e32 v218, 16, v205
	v_and_b32_e32 v219, 0xffff0000, v205
	v_pk_mul_f32 v[204:205], v[220:221], v[220:221]
	v_pk_mul_f32 v[200:201], v[218:219], v[218:219]
	v_add_f32_e32 v204, v222, v204
	v_add_f32_e32 v204, v205, v204
	v_and_b32_e32 v216, 0xffff0000, v206
	v_lshlrev_b32_e32 v217, 16, v206
	v_add_f32_e32 v200, v200, v204
	v_pk_mul_f32 v[140:141], v[216:217], v[216:217]
	v_add_f32_e32 v200, v201, v200
	v_and_b32_e32 v206, 0xffff0000, v207
	v_lshlrev_b32_e32 v207, 16, v207
	v_add_f32_e32 v141, v141, v200
	v_pk_mul_f32 v[196:197], v[206:207], v[206:207]
	v_add_f32_e32 v140, v140, v141
	v_add_f32_e32 v140, v197, v140
	v_add_f32_e32 v140, v196, v140
	ds_bpermute_b32 v141, v195, v140
	v_xor_b32_e32 v195, 32, v247
	v_cmp_lt_i32_e32 vcc, v195, v226
	v_or_b32_e32 v205, s48, v194
	v_mul_lo_u32 v194, v205, s26
	v_cndmask_b32_e32 v195, v247, v195, vcc
	v_lshlrev_b32_e32 v222, 2, v195
	s_waitcnt lgkmcnt(0)
	v_add_f32_e32 v140, v140, v141
	ds_bpermute_b32 v141, v222, v140
	v_add_u32_e32 v195, v194, v172
	v_add_u32_e32 v194, v174, v194
	s_waitcnt lgkmcnt(0)
; #define wt16(p, v) wt16b(WSB, (p), (v))
; __device__ __forceinline__ u32x4 pack8(const float (&f)[8]) { u32x4 v; v.x = cvt_pk_bf16(f[0], f[1]); v.y = cvt_pk_bf16(f[2], f[3]); v.z = cvt_pk_bf16(f[4], f[5]); v.w = cvt_pk_bf16(f[6], f[7]); return v; }
;     __device__ __forceinline__ void operator()(const f32x4 (&acc)[2][2][4][2], const pg8::Unit& u, int wr, int wc, int fr, int fq) const {
;     ...
;                     const float rk = rsqrtf(ssn * (1.f / 96.f) + EPS);
;                     bf16_t* kb = Kf + ((size_t)(b * 8 + head) * SEQ + s) * 96;
; #pragma unroll
;                     for (int bj = 0; bj < 2; ++bj) {
;                         float o[8];
; #pragma unroll
;                         for (int e = 0; e < 8; ++e) o[e] = v[bj][e] * rk * khn[32 * bj + 8 * fq + e];
;                         wt16(kb + 32 * bj + 8 * fq, pack8(o));
;                     }
;                     float o[8];
; #pragma unroll
;                     for (int e = 0; e < 8; ++e) {
;                         const float mine = pe[e] * rk * khn[64 + 8 * fq + e];
;                         const float other = __shfl_xor(mine, 32);
;                         const float2 c = cs[(size_t)row * 16 + ((8 * fq + e) & 15)];
;                         o[e] = (fq < 2) ? (mine * c.x - other * c.y) : (other * c.y + mine * c.x);
;                     }
;                     wt16(kb + 64 + 8 * fq, pack8(o));
	v_add_f32_e32 v140, v140, v141
	v_fmamk_f32 v140, v140, 0x3c2aaaab, v245
	v_mul_f32_e32 v141, 0x4b800000, v140
	v_cmp_gt_f32_e32 vcc, s83, v140
	s_nop 1
	v_cndmask_b32_e32 v140, v140, v141, vcc
	v_rsq_f32_e32 v140, v140
	s_nop 0
	v_mul_f32_e32 v141, 0x45800000, v140
	v_cndmask_b32_e32 v204, v140, v141, vcc
	v_pk_mul_f32 v[140:141], v[146:147], v[204:205] op_sel_hi:[1,0]
	v_pk_mul_f32 v[146:147], v[148:149], v[204:205] op_sel_hi:[1,0]
	v_pk_mul_f32 v[148:149], v[150:151], v[204:205] op_sel_hi:[1,0]
	v_pk_mul_f32 v[150:151], v[152:153], v[204:205] op_sel_hi:[1,0]
	v_pk_mul_f32 v[140:141], v[208:209], v[140:141]
	v_pk_mul_f32 v[152:153], v[210:211], v[146:147]
	v_pk_mul_f32 v[148:149], v[212:213], v[148:149]
	v_pk_mul_f32 v[150:151], v[214:215], v[150:151]
	v_cvt_pk_bf16_f32 v146, v140, v141
	v_cvt_pk_bf16_f32 v147, v152, v153
	v_cvt_pk_bf16_f32 v148, v148, v149
	v_cvt_pk_bf16_f32 v149, v150, v151
	v_mov_b32_e32 v228, v146
	v_mov_b32_e32 v229, v147
	v_mov_b32_e32 v230, v148
	v_mov_b32_e32 v231, v149
	v_mov_b32_e32 v236, v195
	global_load_dwordx4 v[146:149], v[170:171], off offset:128
	s_nop 0
	global_load_dwordx4 v[150:153], v[170:171], off offset:144
	v_lshlrev_b64 v[140:141], 7, v[198:199]
	v_lshl_add_u64 v[198:199], v[168:169], 0, v[140:141]
	v_pk_mul_f32 v[140:141], v[202:203], v[204:205] op_sel_hi:[1,0]
	v_pk_mul_f32 v[138:139], v[138:139], v[204:205] op_sel_hi:[1,0]
	v_pk_mul_f32 v[134:135], v[134:135], v[204:205] op_sel_hi:[1,0]
	v_pk_mul_f32 v[136:137], v[136:137], v[204:205] op_sel_hi:[1,0]
	v_mov_b64_e32 v[202:203], s[2:3]
	v_mad_u64_u32 v[202:203], s[2:3], v205, s26, v[202:203]
	v_mad_i32_i24 v203, s49, v243, v203
	v_lshl_add_u64 v[208:209], v[202:203], 0, v[0:1]
	v_pk_mul_f32 v[202:203], v[204:205], v[220:221] op_sel_hi:[0,1]
	v_pk_mul_f32 v[210:211], v[204:205], v[218:219] op_sel_hi:[0,1]
	v_pk_mul_f32 v[212:213], v[204:205], v[216:217] op_sel_hi:[0,1]
	v_pk_mul_f32 v[204:205], v[204:205], v[206:207] op_sel_hi:[0,1]
	s_waitcnt vmcnt(1)
	v_pk_mul_f32 v[140:141], v[146:147], v[140:141]
	v_pk_mul_f32 v[138:139], v[148:149], v[138:139]
	s_waitcnt vmcnt(0)
	v_pk_mul_f32 v[146:147], v[150:151], v[134:135]
	v_pk_mul_f32 v[148:149], v[152:153], v[136:137]
	v_cvt_pk_bf16_f32 v134, v140, v141
	v_cvt_pk_bf16_f32 v135, v138, v139
	v_cvt_pk_bf16_f32 v136, v146, v147
	v_cvt_pk_bf16_f32 v137, v148, v149
	v_mov_b32_e32 v232, v134
	v_mov_b32_e32 v233, v135
	v_mov_b32_e32 v234, v136
	v_mov_b32_e32 v235, v137
	v_mov_b32_e32 v237, v194
	global_load_dwordx4 v[134:137], v[170:171], off offset:256
	s_nop 0
	global_load_dwordx4 v[138:141], v[198:199], off
	global_load_dwordx4 v[146:149], v[198:199], off offset:16
	global_load_dwordx4 v[150:153], v[170:171], off offset:272
	global_load_dwordx4 v[194:197], v[198:199], off offset:32
	s_nop 0
	global_load_dwordx4 v[198:201], v[198:199], off offset:48
	s_waitcnt vmcnt(5)
	v_pk_mul_f32 v[134:135], v[202:203], v[134:135]
	s_waitcnt vmcnt(4)
	v_mov_b32_e32 v202, v138
	v_mov_b32_e32 v203, v140
	v_mov_b32_e32 v140, v139
	v_pk_mul_f32 v[136:137], v[210:211], v[136:137]
	s_waitcnt vmcnt(3)
	v_mov_b32_e32 v138, v146
	v_mov_b32_e32 v139, v148
	v_mov_b32_e32 v148, v147
	s_waitcnt vmcnt(2)
	v_pk_mul_f32 v[146:147], v[212:213], v[150:151] op_sel:[1,0] op_sel_hi:[0,1]
	v_pk_mul_f32 v[152:153], v[204:205], v[152:153] op_sel:[1,0] op_sel_hi:[0,1]
	ds_bpermute_b32 v204, v222, v134
	ds_bpermute_b32 v205, v222, v135
	ds_bpermute_b32 v206, v222, v136
	ds_bpermute_b32 v207, v222, v137
	ds_bpermute_b32 v210, v222, v146
	ds_bpermute_b32 v211, v222, v147
	ds_bpermute_b32 v212, v222, v152
	ds_bpermute_b32 v213, v222, v153
	s_waitcnt vmcnt(1)
	v_mov_b32_e32 v151, v196
	v_mov_b32_e32 v196, v195
	s_waitcnt vmcnt(0)
	buffer_store_dwordx4 v[228:231], v236, s[56:59], 0 offen sc1
	buffer_store_dwordx4 v[232:235], v237, s[56:59], 0 offen sc1
	v_mov_b32_e32 v195, v200
	v_mov_b32_e32 v200, v199
	v_mov_b32_e32 v150, v194
	v_mov_b32_e32 v194, v198
	s_waitcnt lgkmcnt(6)
	v_pk_mul_f32 v[140:141], v[140:141], v[204:205]
	s_waitcnt lgkmcnt(4)
	v_pk_mul_f32 v[148:149], v[148:149], v[206:207]
	s_waitcnt lgkmcnt(2)
	v_pk_mul_f32 v[196:197], v[196:197], v[210:211]
	s_waitcnt lgkmcnt(0)
	v_pk_mul_f32 v[198:199], v[200:201], v[212:213]
	v_cndmask_b32_e64 v141, v141, -v141, s[40:41]
	v_cndmask_b32_e64 v140, v140, -v140, s[40:41]
	v_cndmask_b32_e64 v149, v149, -v149, s[40:41]
	v_cndmask_b32_e64 v148, v148, -v148, s[40:41]
	v_cndmask_b32_e64 v197, v197, -v197, s[40:41]
	v_cndmask_b32_e64 v196, v196, -v196, s[40:41]
	v_cndmask_b32_e64 v199, v199, -v199, s[40:41]
	v_cndmask_b32_e64 v198, v198, -v198, s[40:41]
	v_pk_fma_f32 v[202:203], v[134:135], v[202:203], v[140:141]
	v_pk_fma_f32 v[138:139], v[136:137], v[138:139], v[148:149]
	v_pk_fma_f32 v[134:135], v[146:147], v[150:151], v[196:197]
	v_pk_fma_f32 v[136:137], v[152:153], v[194:195], v[198:199]
	v_lshl_add_u64 v[204:205], v[208:209], 0, s[80:81]

;     __device__ __forceinline__ void operator()(const f32x4 (&acc)[2][2][4][2], const pg8::Unit& u, int wr, int wc, int fr, int fq) const {
;     ...
;                 if (pn < 2) {
;                     const int head = 4 * pn + wc;
;                     float ssn = 0.f;
; #pragma unroll
;                     for (int bj = 0; bj < 2; ++bj)
; #pragma unroll
;                         for (int e = 0; e < 8; ++e) ssn += v[bj][e] * v[bj][e];
;                     float pe[8]; unpack8(*(const u32x4*)(U + (size_t)row * NU + UPE + 8 * fq), pe);
; #pragma unroll
;                     for (int e = 0; e < 8; ++e) ssn += pe[e] * pe[e];
;                     ssn += __shfl_xor(ssn, 16); ssn += __shfl_xor(ssn, 32);
.LBB0_139:
	v_pk_mul_f32 v[134:135], v[118:119], v[136:137] op_sel_hi:[1,0]
	v_pk_mul_f32 v[118:119], v[120:121], v[136:137] op_sel_hi:[1,0]
	v_pk_mul_f32 v[114:115], v[114:115], v[136:137] op_sel_hi:[1,0]
	s_andn2_b64 vcc, exec, s[2:3]
	v_pk_mul_f32 v[116:117], v[116:117], v[136:137] op_sel_hi:[1,0]
	s_cbranch_vccnz .LBB0_141
	v_mov_b64_e32 v[120:121], s[70:71]
	v_mad_i64_i32 v[120:121], s[2:3], v192, s85, v[120:121]
	v_lshl_add_u64 v[120:121], v[120:121], 0, v[0:1]
	v_add_co_u32_e32 v120, vcc, 0x1000, v120
	v_pk_mul_f32 v[154:155], v[128:129], v[128:129]
	s_nop 0
	v_addc_co_u32_e32 v121, vcc, 0, v121, vcc
	global_load_dwordx4 v[138:141], v[120:121], off offset:1792
	global_load_dwordx4 v[146:149], v[170:171], off
	global_load_dwordx4 v[150:153], v[170:171], off offset:16
	v_pk_mul_f32 v[120:121], v[126:127], v[126:127]
	v_pk_mul_f32 v[156:157], v[122:123], v[122:123]
	v_add_f32_e32 v120, v120, v121
	v_add_f32_e32 v120, v154, v120
	v_add_f32_e32 v120, v155, v120
	v_add_f32_e32 v120, v156, v120
	v_pk_mul_f32 v[194:195], v[124:125], v[124:125]
	v_add_f32_e32 v120, v157, v120
	v_add_f32_e32 v120, v194, v120
	v_pk_mul_f32 v[196:197], v[134:135], v[134:135]
	v_add_f32_e32 v120, v195, v120
	v_add_f32_e32 v120, v196, v120
	v_pk_mul_f32 v[198:199], v[118:119], v[118:119]
	v_add_f32_e32 v120, v197, v120
	v_add_f32_e32 v120, v198, v120
	v_pk_mul_f32 v[200:201], v[114:115], v[114:115]
	v_add_f32_e32 v120, v199, v120
	v_add_f32_e32 v120, v200, v120
	v_pk_mul_f32 v[202:203], v[116:117], v[116:117]
	v_add_f32_e32 v120, v201, v120
	v_add_f32_e32 v120, v202, v120
	v_and_b32_e32 v204, 64, v247
	v_add_f32_e32 v200, v203, v120
	v_xor_b32_e32 v136, 16, v247
	v_add_u32_e32 v204, 64, v204
	v_cmp_lt_i32_e32 vcc, v136, v204
	s_movk_i32 s26, 0xc0
	s_mov_b32 s58, s62
	v_cndmask_b32_e32 v121, v247, v136, vcc
	v_lshlrev_b32_e32 v136, 2, v121
	s_mov_b32 s59, s63
	v_readlane_b32 s2, v253, 32
	v_readlane_b32 s3, v253, 33
	s_waitcnt vmcnt(0)
	v_lshlrev_b32_e32 v196, 16, v138
	v_and_b32_e32 v197, 0xffff0000, v138
	v_pk_mul_f32 v[198:199], v[196:197], v[196:197]
	v_lshlrev_b32_e32 v194, 16, v139
	v_and_b32_e32 v195, 0xffff0000, v139
	v_add_f32_e32 v198, v200, v198
	v_and_b32_e32 v154, 0xffff0000, v140
	v_lshlrev_b32_e32 v155, 16, v140
	v_and_b32_e32 v156, 0xffff0000, v141
	v_lshlrev_b32_e32 v157, 16, v141
	v_pk_mul_f32 v[140:141], v[194:195], v[194:195]
	v_add_f32_e32 v198, v199, v198
	v_add_f32_e32 v140, v140, v198
	v_pk_mul_f32 v[120:121], v[154:155], v[154:155]
	v_add_f32_e32 v140, v141, v140
	v_add_f32_e32 v121, v121, v140
	v_pk_mul_f32 v[138:139], v[156:157], v[156:157]
	v_add_f32_e32 v120, v120, v121
	v_add_f32_e32 v120, v139, v120
	v_add_f32_e32 v120, v138, v120
	ds_bpermute_b32 v121, v136, v120
	v_xor_b32_e32 v136, 32, v247
	v_cmp_lt_i32_e32 vcc, v136, v204
	v_or_b32_e32 v200, s48, v137
	s_waitcnt lgkmcnt(0)
	v_add_f32_e32 v120, v120, v121
	v_cndmask_b32_e32 v136, v247, v136, vcc
	v_lshlrev_b32_e32 v199, 2, v136
	ds_bpermute_b32 v121, v199, v120
	v_mul_lo_u32 v136, v200, s26
	v_add_u32_e32 v137, v136, v172
	v_add_u32_e32 v136, v174, v136
	s_waitcnt lgkmcnt(0)
; #define wt16(p, v) wt16b(WSB, (p), (v))
; __device__ __forceinline__ u32x4 pack8(const float (&f)[8]) { u32x4 v; v.x = cvt_pk_bf16(f[0], f[1]); v.y = cvt_pk_bf16(f[2], f[3]); v.z = cvt_pk_bf16(f[4], f[5]); v.w = cvt_pk_bf16(f[6], f[7]); return v; }
;     __device__ __forceinline__ void operator()(const f32x4 (&acc)[2][2][4][2], const pg8::Unit& u, int wr, int wc, int fr, int fq) const {
;     ...
;                     const float rk = rsqrtf(ssn * (1.f / 96.f) + EPS);
;                     bf16_t* kb = Kf + ((size_t)(b * 8 + head) * SEQ + s) * 96;
; #pragma unroll
;                     for (int bj = 0; bj < 2; ++bj) {
;                         float o[8];
; #pragma unroll
;                         for (int e = 0; e < 8; ++e) o[e] = v[bj][e] * rk * khn[32 * bj + 8 * fq + e];
;                         wt16(kb + 32 * bj + 8 * fq, pack8(o));
;                     }
;                     float o[8];
; #pragma unroll
;                     for (int e = 0; e < 8; ++e) {
;                         const float mine = pe[e] * rk * khn[64 + 8 * fq + e];
;                         const float other = __shfl_xor(mine, 32);
;                         const float2 c = cs[(size_t)row * 16 + ((8 * fq + e) & 15)];
;                         o[e] = (fq < 2) ? (mine * c.x - other * c.y) : (other * c.y + mine * c.x);
;                     }
;                     wt16(kb + 64 + 8 * fq, pack8(o));
	v_add_f32_e32 v120, v120, v121
	v_fmamk_f32 v120, v120, 0x3c2aaaab, v245
	v_mul_f32_e32 v121, 0x4b800000, v120
	v_cmp_gt_f32_e32 vcc, s83, v120
	s_nop 1
	v_cndmask_b32_e32 v120, v120, v121, vcc
	v_rsq_f32_e32 v120, v120
	s_nop 0
	v_mul_f32_e32 v121, 0x45800000, v120
	v_cndmask_b32_e32 v198, v120, v121, vcc
	v_pk_mul_f32 v[120:121], v[126:127], v[198:199] op_sel_hi:[1,0]
	v_pk_mul_f32 v[126:127], v[128:129], v[198:199] op_sel_hi:[1,0]
	v_pk_mul_f32 v[122:123], v[122:123], v[198:199] op_sel_hi:[1,0]
	v_pk_mul_f32 v[124:125], v[124:125], v[198:199] op_sel_hi:[1,0]
	v_pk_mul_f32 v[120:121], v[146:147], v[120:121]
	v_pk_mul_f32 v[126:127], v[148:149], v[126:127]
	v_pk_mul_f32 v[122:123], v[150:151], v[122:123]
	v_pk_mul_f32 v[124:125], v[152:153], v[124:125]
	v_cvt_pk_bf16_f32 v120, v120, v121
	v_cvt_pk_bf16_f32 v121, v126, v127
	v_cvt_pk_bf16_f32 v122, v122, v123
	v_cvt_pk_bf16_f32 v123, v124, v125
	v_mov_b32_e32 v228, v120
	v_mov_b32_e32 v229, v121
	v_mov_b32_e32 v230, v122
	v_mov_b32_e32 v231, v123
	v_mov_b32_e32 v236, v137
	global_load_dwordx4 v[120:123], v[170:171], off offset:128
	s_nop 0
	global_load_dwordx4 v[124:127], v[170:171], off offset:144
	v_lshlrev_b64 v[128:129], 7, v[192:193]
	v_lshl_add_u64 v[138:139], v[168:169], 0, v[128:129]
	v_pk_mul_f32 v[128:129], v[134:135], v[198:199] op_sel_hi:[1,0]
	v_pk_mul_f32 v[118:119], v[118:119], v[198:199] op_sel_hi:[1,0]
	v_pk_mul_f32 v[114:115], v[114:115], v[198:199] op_sel_hi:[1,0]
	v_pk_mul_f32 v[116:117], v[116:117], v[198:199] op_sel_hi:[1,0]
	v_pk_mul_f32 v[148:149], v[198:199], v[196:197] op_sel_hi:[0,1]
	v_pk_mul_f32 v[150:151], v[198:199], v[194:195] op_sel_hi:[0,1]
	v_pk_mul_f32 v[152:153], v[198:199], v[154:155] op_sel_hi:[0,1]
	v_pk_mul_f32 v[154:155], v[198:199], v[156:157] op_sel_hi:[0,1]
	v_mov_b64_e32 v[146:147], s[2:3]
	v_mad_u64_u32 v[146:147], s[2:3], v200, s26, v[146:147]
	v_mad_i32_i24 v147, s49, v243, v147
	v_lshl_add_u64 v[146:147], v[146:147], 0, v[0:1]
	s_waitcnt vmcnt(1)
	v_pk_mul_f32 v[120:121], v[120:121], v[128:129]
	v_pk_mul_f32 v[118:119], v[122:123], v[118:119]
	s_waitcnt vmcnt(0)
	v_pk_mul_f32 v[122:123], v[124:125], v[114:115]
	v_pk_mul_f32 v[124:125], v[126:127], v[116:117]
	v_cvt_pk_bf16_f32 v114, v120, v121
	v_cvt_pk_bf16_f32 v115, v118, v119
	v_cvt_pk_bf16_f32 v116, v122, v123
	v_cvt_pk_bf16_f32 v117, v124, v125
	v_mov_b32_e32 v232, v114
	v_mov_b32_e32 v233, v115
	v_mov_b32_e32 v234, v116
	v_mov_b32_e32 v235, v117
	v_mov_b32_e32 v237, v136
	global_load_dwordx4 v[114:117], v[170:171], off offset:256
	s_nop 0
	global_load_dwordx4 v[118:121], v[138:139], off
	global_load_dwordx4 v[122:125], v[138:139], off offset:16
	global_load_dwordx4 v[126:129], v[170:171], off offset:272
	global_load_dwordx4 v[134:137], v[138:139], off offset:32
	s_nop 0
	global_load_dwordx4 v[138:141], v[138:139], off offset:48
	s_waitcnt vmcnt(5)
	v_pk_mul_f32 v[114:115], v[148:149], v[114:115]
	s_waitcnt vmcnt(4)
	v_mov_b32_e32 v148, v118
	v_mov_b32_e32 v149, v120
	v_mov_b32_e32 v120, v119
	v_pk_mul_f32 v[116:117], v[150:151], v[116:117]
	s_waitcnt vmcnt(3)
	v_mov_b32_e32 v118, v122
	v_mov_b32_e32 v119, v124
	v_mov_b32_e32 v124, v123
	s_waitcnt vmcnt(2)
	v_pk_mul_f32 v[122:123], v[152:153], v[126:127] op_sel:[1,0] op_sel_hi:[0,1]
	v_pk_mul_f32 v[128:129], v[154:155], v[128:129] op_sel:[1,0] op_sel_hi:[0,1]
	s_waitcnt vmcnt(1)
	v_mov_b32_e32 v126, v134
	v_mov_b32_e32 v127, v136
	v_mov_b32_e32 v136, v135
	ds_bpermute_b32 v134, v199, v114
	ds_bpermute_b32 v135, v199, v115
	ds_bpermute_b32 v152, v199, v116
	ds_bpermute_b32 v153, v199, v117
	ds_bpermute_b32 v154, v199, v122
	ds_bpermute_b32 v155, v199, v123
	ds_bpermute_b32 v156, v199, v128
	ds_bpermute_b32 v157, v199, v129
	s_waitcnt vmcnt(0)
	buffer_store_dwordx4 v[228:231], v236, s[56:59], 0 offen sc1
	buffer_store_dwordx4 v[232:235], v237, s[56:59], 0 offen sc1
	v_mov_b32_e32 v151, v140
	v_mov_b32_e32 v140, v139
	s_waitcnt lgkmcnt(6)
	v_pk_mul_f32 v[120:121], v[120:121], v[134:135]
	s_waitcnt lgkmcnt(4)
	v_pk_mul_f32 v[124:125], v[124:125], v[152:153]
	s_waitcnt lgkmcnt(2)
	v_pk_mul_f32 v[134:135], v[136:137], v[154:155]
	s_waitcnt lgkmcnt(0)
	v_pk_mul_f32 v[136:137], v[140:141], v[156:157]
	v_mov_b32_e32 v150, v138
	v_cndmask_b32_e64 v121, v121, -v121, s[40:41]
	v_cndmask_b32_e64 v120, v120, -v120, s[40:41]
	v_cndmask_b32_e64 v125, v125, -v125, s[40:41]
	v_cndmask_b32_e64 v124, v124, -v124, s[40:41]
	v_cndmask_b32_e64 v139, v135, -v135, s[40:41]
	v_cndmask_b32_e64 v138, v134, -v134, s[40:41]
	v_cndmask_b32_e64 v137, v137, -v137, s[40:41]
	v_cndmask_b32_e64 v136, v136, -v136, s[40:41]
	v_pk_fma_f32 v[134:135], v[114:115], v[148:149], v[120:121]
	v_pk_fma_f32 v[118:119], v[116:117], v[118:119], v[124:125]
	v_pk_fma_f32 v[114:115], v[122:123], v[126:127], v[138:139]
	v_pk_fma_f32 v[116:117], v[128:129], v[150:151], v[136:137]
	v_lshl_add_u64 v[138:139], v[146:147], 0, s[80:81]

;     __device__ __forceinline__ void operator()(const f32x4 (&acc)[2][2][4][2], const pg8::Unit& u, int wr, int wc, int fr, int fq) const {
;     ...
;                 if (pn < 2) {
;                     const int head = 4 * pn + wc;
;                     float ssn = 0.f;
; #pragma unroll
;                     for (int bj = 0; bj < 2; ++bj)
; #pragma unroll
;                         for (int e = 0; e < 8; ++e) ssn += v[bj][e] * v[bj][e];
;                     float pe[8]; unpack8(*(const u32x4*)(U + (size_t)row * NU + UPE + 8 * fq), pe);
; #pragma unroll
;                     for (int e = 0; e < 8; ++e) ssn += pe[e] * pe[e];
;                     ssn += __shfl_xor(ssn, 16); ssn += __shfl_xor(ssn, 32);
.LBB0_143:
	v_pk_mul_f32 v[114:115], v[98:99], v[116:117] op_sel_hi:[1,0]
	v_pk_mul_f32 v[98:99], v[100:101], v[116:117] op_sel_hi:[1,0]
	v_pk_mul_f32 v[94:95], v[94:95], v[116:117] op_sel_hi:[1,0]
	s_andn2_b64 vcc, exec, s[2:3]
	v_pk_mul_f32 v[96:97], v[96:97], v[116:117] op_sel_hi:[1,0]
	s_cbranch_vccnz .LBB0_145
	v_mov_b64_e32 v[100:101], s[70:71]
	v_mad_i64_i32 v[100:101], s[2:3], v190, s85, v[100:101]
	v_lshl_add_u64 v[100:101], v[100:101], 0, v[0:1]
	v_add_co_u32_e32 v100, vcc, 0x1000, v100
	v_pk_mul_f32 v[134:135], v[108:109], v[108:109]
	s_nop 0
	v_addc_co_u32_e32 v101, vcc, 0, v101, vcc
	global_load_dwordx4 v[118:121], v[100:101], off offset:1792
	global_load_dwordx4 v[122:125], v[170:171], off
	global_load_dwordx4 v[126:129], v[170:171], off offset:16
	v_pk_mul_f32 v[100:101], v[106:107], v[106:107]
	v_pk_mul_f32 v[136:137], v[102:103], v[102:103]
	v_add_f32_e32 v100, v100, v101
	v_add_f32_e32 v100, v134, v100
	v_add_f32_e32 v100, v135, v100
	v_add_f32_e32 v100, v136, v100
	v_pk_mul_f32 v[138:139], v[104:105], v[104:105]
	v_add_f32_e32 v100, v137, v100
	v_add_f32_e32 v100, v138, v100
	v_pk_mul_f32 v[140:141], v[114:115], v[114:115]
	v_add_f32_e32 v100, v139, v100
	v_add_f32_e32 v100, v140, v100
	v_pk_mul_f32 v[142:143], v[98:99], v[98:99]
	v_add_f32_e32 v100, v141, v100
	v_add_f32_e32 v100, v142, v100
	v_pk_mul_f32 v[144:145], v[94:95], v[94:95]
	v_add_f32_e32 v100, v143, v100
	v_add_f32_e32 v100, v144, v100
	v_pk_mul_f32 v[146:147], v[96:97], v[96:97]
	v_add_f32_e32 v100, v145, v100
	v_add_f32_e32 v100, v146, v100
	v_and_b32_e32 v148, 64, v247
	v_add_f32_e32 v144, v147, v100
	v_xor_b32_e32 v116, 16, v247
	v_add_u32_e32 v148, 64, v148
	v_cmp_lt_i32_e32 vcc, v116, v148
	s_movk_i32 s26, 0xc0
	s_mov_b32 s58, s62
	v_cndmask_b32_e32 v101, v247, v116, vcc
	v_lshlrev_b32_e32 v116, 2, v101
	s_mov_b32 s59, s63
	v_readlane_b32 s2, v253, 32
	v_readlane_b32 s3, v253, 33
	s_waitcnt vmcnt(0)
	v_lshlrev_b32_e32 v140, 16, v118
	v_and_b32_e32 v141, 0xffff0000, v118
	v_pk_mul_f32 v[142:143], v[140:141], v[140:141]
	v_lshlrev_b32_e32 v138, 16, v119
	v_and_b32_e32 v139, 0xffff0000, v119
	v_add_f32_e32 v142, v144, v142
	v_and_b32_e32 v134, 0xffff0000, v120
	v_lshlrev_b32_e32 v135, 16, v120
	v_and_b32_e32 v136, 0xffff0000, v121
	v_lshlrev_b32_e32 v137, 16, v121
	v_pk_mul_f32 v[120:121], v[138:139], v[138:139]
	v_add_f32_e32 v142, v143, v142
	v_add_f32_e32 v120, v120, v142
	v_pk_mul_f32 v[100:101], v[134:135], v[134:135]
	v_add_f32_e32 v120, v121, v120
	v_add_f32_e32 v101, v101, v120
	v_pk_mul_f32 v[118:119], v[136:137], v[136:137]
	v_add_f32_e32 v100, v100, v101
	v_add_f32_e32 v100, v119, v100
	v_add_f32_e32 v100, v118, v100
	ds_bpermute_b32 v101, v116, v100
	v_xor_b32_e32 v116, 32, v247
	v_cmp_lt_i32_e32 vcc, v116, v148
	v_or_b32_e32 v144, s48, v117
	s_waitcnt lgkmcnt(0)
	v_add_f32_e32 v100, v100, v101
	v_cndmask_b32_e32 v116, v247, v116, vcc
	v_lshlrev_b32_e32 v143, 2, v116
	ds_bpermute_b32 v101, v143, v100
	v_mul_lo_u32 v116, v144, s26
	v_add_u32_e32 v117, v116, v172
	v_add_u32_e32 v116, v174, v116
	s_waitcnt lgkmcnt(0)
; #define wt16(p, v) wt16b(WSB, (p), (v))
; __device__ __forceinline__ u32x4 pack8(const float (&f)[8]) { u32x4 v; v.x = cvt_pk_bf16(f[0], f[1]); v.y = cvt_pk_bf16(f[2], f[3]); v.z = cvt_pk_bf16(f[4], f[5]); v.w = cvt_pk_bf16(f[6], f[7]); return v; }
;     __device__ __forceinline__ void operator()(const f32x4 (&acc)[2][2][4][2], const pg8::Unit& u, int wr, int wc, int fr, int fq) const {
;     ...
;                     const float rk = rsqrtf(ssn * (1.f / 96.f) + EPS);
;                     bf16_t* kb = Kf + ((size_t)(b * 8 + head) * SEQ + s) * 96;
; #pragma unroll
;                     for (int bj = 0; bj < 2; ++bj) {
;                         float o[8];
; #pragma unroll
;                         for (int e = 0; e < 8; ++e) o[e] = v[bj][e] * rk * khn[32 * bj + 8 * fq + e];
;                         wt16(kb + 32 * bj + 8 * fq, pack8(o));
;                     }
;                     float o[8];
; #pragma unroll
;                     for (int e = 0; e < 8; ++e) {
;                         const float mine = pe[e] * rk * khn[64 + 8 * fq + e];
;                         const float other = __shfl_xor(mine, 32);
;                         const float2 c = cs[(size_t)row * 16 + ((8 * fq + e) & 15)];
;                         o[e] = (fq < 2) ? (mine * c.x - other * c.y) : (other * c.y + mine * c.x);
;                     }
;                     wt16(kb + 64 + 8 * fq, pack8(o));
	v_add_f32_e32 v100, v100, v101
	v_fmamk_f32 v100, v100, 0x3c2aaaab, v245
	v_mul_f32_e32 v101, 0x4b800000, v100
	v_cmp_gt_f32_e32 vcc, s83, v100
	s_nop 1
	v_cndmask_b32_e32 v100, v100, v101, vcc
	v_rsq_f32_e32 v100, v100
	s_nop 0
	v_mul_f32_e32 v101, 0x45800000, v100
	v_cndmask_b32_e32 v142, v100, v101, vcc
	v_pk_mul_f32 v[100:101], v[106:107], v[142:143] op_sel_hi:[1,0]
	v_pk_mul_f32 v[106:107], v[108:109], v[142:143] op_sel_hi:[1,0]
	v_pk_mul_f32 v[102:103], v[102:103], v[142:143] op_sel_hi:[1,0]
	v_pk_mul_f32 v[104:105], v[104:105], v[142:143] op_sel_hi:[1,0]
	v_pk_mul_f32 v[100:101], v[122:123], v[100:101]
	v_pk_mul_f32 v[106:107], v[124:125], v[106:107]
	v_pk_mul_f32 v[102:103], v[126:127], v[102:103]
	v_pk_mul_f32 v[104:105], v[128:129], v[104:105]
	v_cvt_pk_bf16_f32 v100, v100, v101
	v_cvt_pk_bf16_f32 v101, v106, v107
	v_cvt_pk_bf16_f32 v102, v102, v103
	v_cvt_pk_bf16_f32 v103, v104, v105
	v_mov_b32_e32 v228, v100
	v_mov_b32_e32 v229, v101
	v_mov_b32_e32 v230, v102
	v_mov_b32_e32 v231, v103
	v_mov_b32_e32 v236, v117
	global_load_dwordx4 v[100:103], v[170:171], off offset:128
	s_nop 0
	global_load_dwordx4 v[104:107], v[170:171], off offset:144
	v_lshlrev_b64 v[108:109], 7, v[190:191]
	v_lshl_add_u64 v[118:119], v[168:169], 0, v[108:109]
	v_pk_mul_f32 v[108:109], v[114:115], v[142:143] op_sel_hi:[1,0]
	v_pk_mul_f32 v[98:99], v[98:99], v[142:143] op_sel_hi:[1,0]
	v_pk_mul_f32 v[94:95], v[94:95], v[142:143] op_sel_hi:[1,0]
	v_pk_mul_f32 v[96:97], v[96:97], v[142:143] op_sel_hi:[1,0]
	v_pk_mul_f32 v[124:125], v[142:143], v[140:141] op_sel_hi:[0,1]
	v_pk_mul_f32 v[126:127], v[142:143], v[138:139] op_sel_hi:[0,1]
	v_pk_mul_f32 v[128:129], v[142:143], v[134:135] op_sel_hi:[0,1]
	v_pk_mul_f32 v[134:135], v[142:143], v[136:137] op_sel_hi:[0,1]
	v_mov_b64_e32 v[122:123], s[2:3]
	v_mad_u64_u32 v[122:123], s[2:3], v144, s26, v[122:123]
	v_mad_i32_i24 v123, s49, v243, v123
	v_lshl_add_u64 v[122:123], v[122:123], 0, v[0:1]
	s_waitcnt vmcnt(1)
	v_pk_mul_f32 v[100:101], v[100:101], v[108:109]
	v_pk_mul_f32 v[98:99], v[102:103], v[98:99]
	s_waitcnt vmcnt(0)
	v_pk_mul_f32 v[102:103], v[104:105], v[94:95]
	v_pk_mul_f32 v[104:105], v[106:107], v[96:97]
	v_cvt_pk_bf16_f32 v94, v100, v101
	v_cvt_pk_bf16_f32 v95, v98, v99
	v_cvt_pk_bf16_f32 v96, v102, v103
	v_cvt_pk_bf16_f32 v97, v104, v105
	v_mov_b32_e32 v232, v94
	v_mov_b32_e32 v233, v95
	v_mov_b32_e32 v234, v96
	v_mov_b32_e32 v235, v97
	v_mov_b32_e32 v237, v116
	global_load_dwordx4 v[94:97], v[170:171], off offset:256
	s_nop 0
	global_load_dwordx4 v[98:101], v[118:119], off
	global_load_dwordx4 v[102:105], v[118:119], off offset:16
	global_load_dwordx4 v[106:109], v[170:171], off offset:272
	global_load_dwordx4 v[114:117], v[118:119], off offset:32
	s_nop 0
	global_load_dwordx4 v[118:121], v[118:119], off offset:48
	s_waitcnt vmcnt(5)
	v_pk_mul_f32 v[94:95], v[124:125], v[94:95]
	s_waitcnt vmcnt(4)
	v_mov_b32_e32 v124, v98
	v_mov_b32_e32 v125, v100
	v_mov_b32_e32 v100, v99
	v_pk_mul_f32 v[96:97], v[126:127], v[96:97]
	s_waitcnt vmcnt(3)
	v_mov_b32_e32 v98, v102
	v_mov_b32_e32 v99, v104
	v_mov_b32_e32 v104, v103
	s_waitcnt vmcnt(2)
	v_pk_mul_f32 v[102:103], v[128:129], v[106:107] op_sel:[1,0] op_sel_hi:[0,1]
	v_pk_mul_f32 v[108:109], v[134:135], v[108:109] op_sel:[1,0] op_sel_hi:[0,1]
	s_waitcnt vmcnt(1)
	v_mov_b32_e32 v106, v114
	v_mov_b32_e32 v107, v116
	v_mov_b32_e32 v116, v115
	ds_bpermute_b32 v114, v143, v94
	ds_bpermute_b32 v115, v143, v95
	ds_bpermute_b32 v128, v143, v96
	ds_bpermute_b32 v129, v143, v97
	ds_bpermute_b32 v134, v143, v102
	ds_bpermute_b32 v135, v143, v103
	ds_bpermute_b32 v136, v143, v108
	ds_bpermute_b32 v137, v143, v109
	s_waitcnt vmcnt(0)
	buffer_store_dwordx4 v[228:231], v236, s[56:59], 0 offen sc1
	buffer_store_dwordx4 v[232:235], v237, s[56:59], 0 offen sc1
	v_mov_b32_e32 v127, v120
	v_mov_b32_e32 v120, v119
	s_waitcnt lgkmcnt(6)
	v_pk_mul_f32 v[100:101], v[100:101], v[114:115]
	s_waitcnt lgkmcnt(4)
	v_pk_mul_f32 v[104:105], v[104:105], v[128:129]
	s_waitcnt lgkmcnt(2)
	v_pk_mul_f32 v[114:115], v[116:117], v[134:135]
	s_waitcnt lgkmcnt(0)
	v_pk_mul_f32 v[116:117], v[120:121], v[136:137]
	v_mov_b32_e32 v126, v118
	v_cndmask_b32_e64 v101, v101, -v101, s[40:41]
	v_cndmask_b32_e64 v100, v100, -v100, s[40:41]
	v_cndmask_b32_e64 v105, v105, -v105, s[40:41]
	v_cndmask_b32_e64 v104, v104, -v104, s[40:41]
	v_cndmask_b32_e64 v119, v115, -v115, s[40:41]
	v_cndmask_b32_e64 v118, v114, -v114, s[40:41]
	v_cndmask_b32_e64 v117, v117, -v117, s[40:41]
	v_cndmask_b32_e64 v116, v116, -v116, s[40:41]
	v_pk_fma_f32 v[114:115], v[94:95], v[124:125], v[100:101]
	v_pk_fma_f32 v[98:99], v[96:97], v[98:99], v[104:105]
	v_pk_fma_f32 v[94:95], v[102:103], v[106:107], v[118:119]
	v_pk_fma_f32 v[96:97], v[108:109], v[126:127], v[116:117]
	v_lshl_add_u64 v[118:119], v[122:123], 0, s[80:81]

;     __device__ __forceinline__ void operator()(const f32x4 (&acc)[2][2][4][2], const pg8::Unit& u, int wr, int wc, int fr, int fq) const {
;     ...
;                 if (pn < 2) {
;                     const int head = 4 * pn + wc;
;                     float ssn = 0.f;
; #pragma unroll
;                     for (int bj = 0; bj < 2; ++bj)
; #pragma unroll
;                         for (int e = 0; e < 8; ++e) ssn += v[bj][e] * v[bj][e];
;                     float pe[8]; unpack8(*(const u32x4*)(U + (size_t)row * NU + UPE + 8 * fq), pe);
; #pragma unroll
;                     for (int e = 0; e < 8; ++e) ssn += pe[e] * pe[e];
;                     ssn += __shfl_xor(ssn, 16); ssn += __shfl_xor(ssn, 32);
.LBB0_147:
	v_pk_mul_f32 v[94:95], v[78:79], v[96:97] op_sel_hi:[1,0]
	v_pk_mul_f32 v[78:79], v[80:81], v[96:97] op_sel_hi:[1,0]
	v_pk_mul_f32 v[74:75], v[74:75], v[96:97] op_sel_hi:[1,0]
	s_andn2_b64 vcc, exec, s[2:3]
	v_pk_mul_f32 v[76:77], v[76:77], v[96:97] op_sel_hi:[1,0]
	s_cbranch_vccnz .LBB0_149
	v_mov_b64_e32 v[80:81], s[70:71]
	v_mad_i64_i32 v[80:81], s[2:3], v188, s85, v[80:81]
	v_lshl_add_u64 v[80:81], v[80:81], 0, v[0:1]
	v_add_co_u32_e32 v80, vcc, 0x1000, v80
	v_pk_mul_f32 v[114:115], v[88:89], v[88:89]
	s_nop 0
	v_addc_co_u32_e32 v81, vcc, 0, v81, vcc
	global_load_dwordx4 v[98:101], v[80:81], off offset:1792
	global_load_dwordx4 v[102:105], v[170:171], off
	global_load_dwordx4 v[106:109], v[170:171], off offset:16
	v_pk_mul_f32 v[80:81], v[86:87], v[86:87]
	v_pk_mul_f32 v[116:117], v[82:83], v[82:83]
	v_add_f32_e32 v80, v80, v81
	v_add_f32_e32 v80, v114, v80
	v_add_f32_e32 v80, v115, v80
	v_add_f32_e32 v80, v116, v80
	v_pk_mul_f32 v[118:119], v[84:85], v[84:85]
	v_add_f32_e32 v80, v117, v80
	v_add_f32_e32 v80, v118, v80
	v_pk_mul_f32 v[120:121], v[94:95], v[94:95]
	v_add_f32_e32 v80, v119, v80
	v_add_f32_e32 v80, v120, v80
	v_pk_mul_f32 v[122:123], v[78:79], v[78:79]
	v_add_f32_e32 v80, v121, v80
	v_add_f32_e32 v80, v122, v80
	v_pk_mul_f32 v[124:125], v[74:75], v[74:75]
	v_add_f32_e32 v80, v123, v80
	v_add_f32_e32 v80, v124, v80
	v_pk_mul_f32 v[126:127], v[76:77], v[76:77]
	v_add_f32_e32 v80, v125, v80
	v_add_f32_e32 v80, v126, v80
	v_and_b32_e32 v128, 64, v247
	v_add_f32_e32 v124, v127, v80
	v_xor_b32_e32 v96, 16, v247
	v_add_u32_e32 v128, 64, v128
	v_cmp_lt_i32_e32 vcc, v96, v128
	s_movk_i32 s26, 0xc0
	s_mov_b32 s58, s62
	v_cndmask_b32_e32 v81, v247, v96, vcc
	v_lshlrev_b32_e32 v96, 2, v81
	s_mov_b32 s59, s63
	v_readlane_b32 s2, v253, 32
	v_readlane_b32 s3, v253, 33
	s_waitcnt vmcnt(0)
	v_lshlrev_b32_e32 v120, 16, v98
	v_and_b32_e32 v121, 0xffff0000, v98
	v_pk_mul_f32 v[122:123], v[120:121], v[120:121]
	v_lshlrev_b32_e32 v118, 16, v99
	v_and_b32_e32 v119, 0xffff0000, v99
	v_add_f32_e32 v122, v124, v122
	v_and_b32_e32 v114, 0xffff0000, v100
	v_lshlrev_b32_e32 v115, 16, v100
	v_and_b32_e32 v116, 0xffff0000, v101
	v_lshlrev_b32_e32 v117, 16, v101
	v_pk_mul_f32 v[100:101], v[118:119], v[118:119]
	v_add_f32_e32 v122, v123, v122
	v_add_f32_e32 v100, v100, v122
	v_pk_mul_f32 v[80:81], v[114:115], v[114:115]
	v_add_f32_e32 v100, v101, v100
	v_add_f32_e32 v81, v81, v100
	v_pk_mul_f32 v[98:99], v[116:117], v[116:117]
	v_add_f32_e32 v80, v80, v81
	v_add_f32_e32 v80, v99, v80
	v_add_f32_e32 v80, v98, v80
	ds_bpermute_b32 v81, v96, v80
	v_xor_b32_e32 v96, 32, v247
	v_cmp_lt_i32_e32 vcc, v96, v128
	v_or_b32_e32 v124, s48, v97
	s_waitcnt lgkmcnt(0)
	v_add_f32_e32 v80, v80, v81
	v_cndmask_b32_e32 v96, v247, v96, vcc
	v_lshlrev_b32_e32 v123, 2, v96
	ds_bpermute_b32 v81, v123, v80
	v_mul_lo_u32 v96, v124, s26
	v_add_u32_e32 v97, v96, v172
	v_add_u32_e32 v96, v174, v96
	s_waitcnt lgkmcnt(0)
; #define wt16(p, v) wt16b(WSB, (p), (v))
; __device__ __forceinline__ u32x4 pack8(const float (&f)[8]) { u32x4 v; v.x = cvt_pk_bf16(f[0], f[1]); v.y = cvt_pk_bf16(f[2], f[3]); v.z = cvt_pk_bf16(f[4], f[5]); v.w = cvt_pk_bf16(f[6], f[7]); return v; }
;     __device__ __forceinline__ void operator()(const f32x4 (&acc)[2][2][4][2], const pg8::Unit& u, int wr, int wc, int fr, int fq) const {
;     ...
;                     const float rk = rsqrtf(ssn * (1.f / 96.f) + EPS);
;                     bf16_t* kb = Kf + ((size_t)(b * 8 + head) * SEQ + s) * 96;
; #pragma unroll
;                     for (int bj = 0; bj < 2; ++bj) {
;                         float o[8];
; #pragma unroll
;                         for (int e = 0; e < 8; ++e) o[e] = v[bj][e] * rk * khn[32 * bj + 8 * fq + e];
;                         wt16(kb + 32 * bj + 8 * fq, pack8(o));
;                     }
;                     float o[8];
; #pragma unroll
;                     for (int e = 0; e < 8; ++e) {
;                         const float mine = pe[e] * rk * khn[64 + 8 * fq + e];
;                         const float other = __shfl_xor(mine, 32);
;                         const float2 c = cs[(size_t)row * 16 + ((8 * fq + e) & 15)];
;                         o[e] = (fq < 2) ? (mine * c.x - other * c.y) : (other * c.y + mine * c.x);
;                     }
;                     wt16(kb + 64 + 8 * fq, pack8(o));
	v_add_f32_e32 v80, v80, v81
	v_fmamk_f32 v80, v80, 0x3c2aaaab, v245
	v_mul_f32_e32 v81, 0x4b800000, v80
	v_cmp_gt_f32_e32 vcc, s83, v80
	s_nop 1
	v_cndmask_b32_e32 v80, v80, v81, vcc
	v_rsq_f32_e32 v80, v80
	s_nop 0
	v_mul_f32_e32 v81, 0x45800000, v80
	v_cndmask_b32_e32 v122, v80, v81, vcc
	v_pk_mul_f32 v[80:81], v[86:87], v[122:123] op_sel_hi:[1,0]
	v_pk_mul_f32 v[86:87], v[88:89], v[122:123] op_sel_hi:[1,0]
	v_pk_mul_f32 v[82:83], v[82:83], v[122:123] op_sel_hi:[1,0]
	v_pk_mul_f32 v[84:85], v[84:85], v[122:123] op_sel_hi:[1,0]
	v_pk_mul_f32 v[80:81], v[102:103], v[80:81]
	v_pk_mul_f32 v[86:87], v[104:105], v[86:87]
	v_pk_mul_f32 v[82:83], v[106:107], v[82:83]
	v_pk_mul_f32 v[84:85], v[108:109], v[84:85]
	v_cvt_pk_bf16_f32 v80, v80, v81
	v_cvt_pk_bf16_f32 v81, v86, v87
	v_cvt_pk_bf16_f32 v82, v82, v83
	v_cvt_pk_bf16_f32 v83, v84, v85
	v_mov_b32_e32 v228, v80
	v_mov_b32_e32 v229, v81
	v_mov_b32_e32 v230, v82
	v_mov_b32_e32 v231, v83
	v_mov_b32_e32 v236, v97
	global_load_dwordx4 v[80:83], v[170:171], off offset:128
	s_nop 0
	global_load_dwordx4 v[84:87], v[170:171], off offset:144
	v_lshlrev_b64 v[88:89], 7, v[188:189]
	v_lshl_add_u64 v[98:99], v[168:169], 0, v[88:89]
	v_pk_mul_f32 v[88:89], v[94:95], v[122:123] op_sel_hi:[1,0]
	v_pk_mul_f32 v[78:79], v[78:79], v[122:123] op_sel_hi:[1,0]
	v_pk_mul_f32 v[74:75], v[74:75], v[122:123] op_sel_hi:[1,0]
	v_pk_mul_f32 v[76:77], v[76:77], v[122:123] op_sel_hi:[1,0]
	v_pk_mul_f32 v[104:105], v[122:123], v[120:121] op_sel_hi:[0,1]
	v_pk_mul_f32 v[106:107], v[122:123], v[118:119] op_sel_hi:[0,1]
	v_pk_mul_f32 v[108:109], v[122:123], v[114:115] op_sel_hi:[0,1]
	v_pk_mul_f32 v[114:115], v[122:123], v[116:117] op_sel_hi:[0,1]
	v_mov_b64_e32 v[102:103], s[2:3]
	v_mad_u64_u32 v[102:103], s[2:3], v124, s26, v[102:103]
	v_mad_i32_i24 v103, s49, v243, v103
	v_lshl_add_u64 v[102:103], v[102:103], 0, v[0:1]
	s_waitcnt vmcnt(1)
	v_pk_mul_f32 v[80:81], v[80:81], v[88:89]
	v_pk_mul_f32 v[78:79], v[82:83], v[78:79]
	s_waitcnt vmcnt(0)
	v_pk_mul_f32 v[82:83], v[84:85], v[74:75]
	v_pk_mul_f32 v[84:85], v[86:87], v[76:77]
	v_cvt_pk_bf16_f32 v74, v80, v81
	v_cvt_pk_bf16_f32 v75, v78, v79
	v_cvt_pk_bf16_f32 v76, v82, v83
	v_cvt_pk_bf16_f32 v77, v84, v85
	v_mov_b32_e32 v232, v74
	v_mov_b32_e32 v233, v75
	v_mov_b32_e32 v234, v76
	v_mov_b32_e32 v235, v77
	v_mov_b32_e32 v237, v96
	global_load_dwordx4 v[74:77], v[170:171], off offset:256
	s_nop 0
	global_load_dwordx4 v[78:81], v[98:99], off
	global_load_dwordx4 v[82:85], v[98:99], off offset:16
	global_load_dwordx4 v[86:89], v[170:171], off offset:272
	global_load_dwordx4 v[94:97], v[98:99], off offset:32
	s_nop 0
	global_load_dwordx4 v[98:101], v[98:99], off offset:48
	s_waitcnt vmcnt(5)
	v_pk_mul_f32 v[74:75], v[104:105], v[74:75]
	s_waitcnt vmcnt(4)
	v_mov_b32_e32 v104, v78
	v_mov_b32_e32 v105, v80
	v_mov_b32_e32 v80, v79
	v_pk_mul_f32 v[76:77], v[106:107], v[76:77]
	s_waitcnt vmcnt(3)
	v_mov_b32_e32 v78, v82
	v_mov_b32_e32 v79, v84
	v_mov_b32_e32 v84, v83
	s_waitcnt vmcnt(2)
	v_pk_mul_f32 v[82:83], v[108:109], v[86:87] op_sel:[1,0] op_sel_hi:[0,1]
	v_pk_mul_f32 v[88:89], v[114:115], v[88:89] op_sel:[1,0] op_sel_hi:[0,1]
	s_waitcnt vmcnt(1)
	v_mov_b32_e32 v86, v94
	v_mov_b32_e32 v87, v96
	v_mov_b32_e32 v96, v95
	ds_bpermute_b32 v94, v123, v74
	ds_bpermute_b32 v95, v123, v75
	ds_bpermute_b32 v108, v123, v76
	ds_bpermute_b32 v109, v123, v77
	ds_bpermute_b32 v114, v123, v82
	ds_bpermute_b32 v115, v123, v83
	ds_bpermute_b32 v116, v123, v88
	ds_bpermute_b32 v117, v123, v89
	s_waitcnt vmcnt(0)
	buffer_store_dwordx4 v[228:231], v236, s[56:59], 0 offen sc1
	buffer_store_dwordx4 v[232:235], v237, s[56:59], 0 offen sc1
	v_mov_b32_e32 v107, v100
	v_mov_b32_e32 v100, v99
	s_waitcnt lgkmcnt(6)
	v_pk_mul_f32 v[80:81], v[80:81], v[94:95]
	s_waitcnt lgkmcnt(4)
	v_pk_mul_f32 v[84:85], v[84:85], v[108:109]
	s_waitcnt lgkmcnt(2)
	v_pk_mul_f32 v[94:95], v[96:97], v[114:115]
	s_waitcnt lgkmcnt(0)
	v_pk_mul_f32 v[96:97], v[100:101], v[116:117]
	v_mov_b32_e32 v106, v98
	v_cndmask_b32_e64 v81, v81, -v81, s[40:41]
	v_cndmask_b32_e64 v80, v80, -v80, s[40:41]
	v_cndmask_b32_e64 v85, v85, -v85, s[40:41]
	v_cndmask_b32_e64 v84, v84, -v84, s[40:41]
	v_cndmask_b32_e64 v99, v95, -v95, s[40:41]
	v_cndmask_b32_e64 v98, v94, -v94, s[40:41]
	v_cndmask_b32_e64 v97, v97, -v97, s[40:41]
	v_cndmask_b32_e64 v96, v96, -v96, s[40:41]
	v_pk_fma_f32 v[94:95], v[74:75], v[104:105], v[80:81]
	v_pk_fma_f32 v[78:79], v[76:77], v[78:79], v[84:85]
	v_pk_fma_f32 v[74:75], v[82:83], v[86:87], v[98:99]
	v_pk_fma_f32 v[76:77], v[88:89], v[106:107], v[96:97]
	v_lshl_add_u64 v[98:99], v[102:103], 0, s[80:81]

;     __device__ __forceinline__ void operator()(const f32x4 (&acc)[2][2][4][2], const pg8::Unit& u, int wr, int wc, int fr, int fq) const {
;     ...
;                 if (pn < 2) {
;                     const int head = 4 * pn + wc;
;                     float ssn = 0.f;
; #pragma unroll
;                     for (int bj = 0; bj < 2; ++bj)
; #pragma unroll
;                         for (int e = 0; e < 8; ++e) ssn += v[bj][e] * v[bj][e];
;                     float pe[8]; unpack8(*(const u32x4*)(U + (size_t)row * NU + UPE + 8 * fq), pe);
; #pragma unroll
;                     for (int e = 0; e < 8; ++e) ssn += pe[e] * pe[e];
;                     ssn += __shfl_xor(ssn, 16); ssn += __shfl_xor(ssn, 32);
;                     const float rk = rsqrtf(ssn * (1.f / 96.f) + EPS);
;                     bf16_t* kb = Kf + ((size_t)(b * 8 + head) * SEQ + s) * 96;
.LBB0_151:
	v_add_u32_e32 v62, s28, v80
	v_ashrrev_i32_e32 v63, 31, v62
	v_lshlrev_b64 v[62:63], 11, v[62:63]
	v_pk_mul_f32 v[80:81], v[58:59], v[82:83] op_sel_hi:[1,0]
	v_pk_mul_f32 v[58:59], v[60:61], v[82:83] op_sel_hi:[1,0]
	v_pk_mul_f32 v[54:55], v[54:55], v[82:83] op_sel_hi:[1,0]
	s_andn2_b64 vcc, exec, s[2:3]
	v_pk_mul_f32 v[56:57], v[56:57], v[82:83] op_sel_hi:[1,0]
	s_cbranch_vccnz .LBB0_153
	v_mov_b64_e32 v[60:61], s[70:71]
	v_mad_i64_i32 v[60:61], s[2:3], v186, s85, v[60:61]
	v_lshl_add_u64 v[60:61], v[60:61], 0, v[0:1]
	v_add_co_u32_e32 v60, vcc, 0x1000, v60
	v_pk_mul_f32 v[88:89], v[68:69], v[68:69]
	s_nop 0
	v_addc_co_u32_e32 v61, vcc, 0, v61, vcc
	global_load_dwordx4 v[84:87], v[60:61], off offset:1792
	global_load_dwordx4 v[94:97], v[170:171], off
	global_load_dwordx4 v[98:101], v[170:171], off offset:16
	v_pk_mul_f32 v[60:61], v[66:67], v[66:67]
	v_pk_mul_f32 v[102:103], v[76:77], v[76:77]
	v_add_f32_e32 v60, v60, v61
	v_add_f32_e32 v60, v88, v60
	v_add_f32_e32 v60, v89, v60
	v_add_f32_e32 v60, v102, v60
	v_pk_mul_f32 v[104:105], v[78:79], v[78:79]
	v_add_f32_e32 v60, v103, v60
	v_add_f32_e32 v60, v104, v60
	v_pk_mul_f32 v[106:107], v[80:81], v[80:81]
	v_add_f32_e32 v60, v105, v60
	v_add_f32_e32 v60, v106, v60
	v_pk_mul_f32 v[108:109], v[58:59], v[58:59]
	v_add_f32_e32 v60, v107, v60
	v_add_f32_e32 v60, v108, v60
	v_pk_mul_f32 v[110:111], v[54:55], v[54:55]
	v_add_f32_e32 v60, v109, v60
	v_add_f32_e32 v60, v110, v60
	v_pk_mul_f32 v[112:113], v[56:57], v[56:57]
	v_add_f32_e32 v60, v111, v60
	v_add_f32_e32 v60, v112, v60
	v_and_b32_e32 v82, 64, v247
	v_add_f32_e32 v110, v113, v60
	v_xor_b32_e32 v75, 16, v247
	v_add_u32_e32 v82, 64, v82
	v_cmp_lt_i32_e32 vcc, v75, v82
	s_movk_i32 s21, 0xc0
	s_mov_b32 s58, s62
	v_cndmask_b32_e32 v61, v247, v75, vcc
	v_lshlrev_b32_e32 v75, 2, v61
	s_mov_b32 s59, s63
	v_readlane_b32 s2, v253, 32
	v_readlane_b32 s3, v253, 33
	s_waitcnt vmcnt(0)
	v_lshlrev_b32_e32 v106, 16, v84
	v_and_b32_e32 v107, 0xffff0000, v84
	v_pk_mul_f32 v[108:109], v[106:107], v[106:107]
	v_lshlrev_b32_e32 v104, 16, v85
	v_and_b32_e32 v105, 0xffff0000, v85
	v_add_f32_e32 v108, v110, v108
	v_and_b32_e32 v88, 0xffff0000, v86
	v_lshlrev_b32_e32 v89, 16, v86
	v_and_b32_e32 v102, 0xffff0000, v87
	v_lshlrev_b32_e32 v103, 16, v87
	v_pk_mul_f32 v[86:87], v[104:105], v[104:105]
	v_add_f32_e32 v108, v109, v108
	v_add_f32_e32 v86, v86, v108
	v_pk_mul_f32 v[60:61], v[88:89], v[88:89]
	v_add_f32_e32 v86, v87, v86
	v_add_f32_e32 v61, v61, v86
	v_pk_mul_f32 v[84:85], v[102:103], v[102:103]
	v_add_f32_e32 v60, v60, v61
	v_add_f32_e32 v60, v85, v60
	v_add_f32_e32 v60, v84, v60
	ds_bpermute_b32 v61, v75, v60
	v_xor_b32_e32 v75, 32, v247
	v_cmp_lt_i32_e32 vcc, v75, v82
	v_or_b32_e32 v109, v62, v83
	v_mul_lo_u32 v82, v109, s21
	v_cndmask_b32_e32 v75, v247, v75, vcc
	v_lshlrev_b32_e32 v75, 2, v75
	s_waitcnt lgkmcnt(0)
	v_add_f32_e32 v60, v60, v61
	ds_bpermute_b32 v61, v75, v60
	v_add_u32_e32 v83, v82, v172
	v_add_u32_e32 v82, v174, v82
	s_waitcnt lgkmcnt(0)
; #define wt16(p, v) wt16b(WSB, (p), (v))
; __device__ __forceinline__ u32x4 pack8(const float (&f)[8]) { u32x4 v; v.x = cvt_pk_bf16(f[0], f[1]); v.y = cvt_pk_bf16(f[2], f[3]); v.z = cvt_pk_bf16(f[4], f[5]); v.w = cvt_pk_bf16(f[6], f[7]); return v; }
;     __device__ __forceinline__ void operator()(const f32x4 (&acc)[2][2][4][2], const pg8::Unit& u, int wr, int wc, int fr, int fq) const {
;     ...
;                     const float rk = rsqrtf(ssn * (1.f / 96.f) + EPS);
;                     bf16_t* kb = Kf + ((size_t)(b * 8 + head) * SEQ + s) * 96;
; #pragma unroll
;                     for (int bj = 0; bj < 2; ++bj) {
;                         float o[8];
; #pragma unroll
;                         for (int e = 0; e < 8; ++e) o[e] = v[bj][e] * rk * khn[32 * bj + 8 * fq + e];
;                         wt16(kb + 32 * bj + 8 * fq, pack8(o));
;                     }
;                     float o[8];
; #pragma unroll
;                     for (int e = 0; e < 8; ++e) {
;                         const float mine = pe[e] * rk * khn[64 + 8 * fq + e];
;                         const float other = __shfl_xor(mine, 32);
;                         const float2 c = cs[(size_t)row * 16 + ((8 * fq + e) & 15)];
;                         o[e] = (fq < 2) ? (mine * c.x - other * c.y) : (other * c.y + mine * c.x);
;                     }
;                     wt16(kb + 64 + 8 * fq, pack8(o));
	v_add_f32_e32 v60, v60, v61
	v_fmamk_f32 v60, v60, 0x3c2aaaab, v245
	v_mul_f32_e32 v61, 0x4b800000, v60
	v_cmp_gt_f32_e32 vcc, s83, v60
	s_nop 1
	v_cndmask_b32_e32 v60, v60, v61, vcc
	v_rsq_f32_e32 v60, v60
	s_nop 0
	v_mul_f32_e32 v61, 0x45800000, v60
	v_cndmask_b32_e32 v108, v60, v61, vcc
	v_pk_mul_f32 v[60:61], v[66:67], v[108:109] op_sel_hi:[1,0]
	v_pk_mul_f32 v[66:67], v[68:69], v[108:109] op_sel_hi:[1,0]
	v_pk_mul_f32 v[68:69], v[76:77], v[108:109] op_sel_hi:[1,0]
	v_pk_mul_f32 v[76:77], v[78:79], v[108:109] op_sel_hi:[1,0]
	v_pk_mul_f32 v[60:61], v[94:95], v[60:61]
	v_pk_mul_f32 v[78:79], v[96:97], v[66:67]
	v_pk_mul_f32 v[68:69], v[98:99], v[68:69]
	v_pk_mul_f32 v[76:77], v[100:101], v[76:77]
	v_cvt_pk_bf16_f32 v66, v60, v61
	v_cvt_pk_bf16_f32 v67, v78, v79
	v_cvt_pk_bf16_f32 v68, v68, v69
	v_cvt_pk_bf16_f32 v69, v76, v77
	v_mov_b32_e32 v228, v66
	v_mov_b32_e32 v229, v67
	v_mov_b32_e32 v230, v68
	v_mov_b32_e32 v231, v69
	v_mov_b32_e32 v236, v83
	global_load_dwordx4 v[66:69], v[170:171], off offset:128
	s_nop 0
	global_load_dwordx4 v[76:79], v[170:171], off offset:144
	v_lshlrev_b64 v[60:61], 7, v[186:187]
	v_lshl_add_u64 v[84:85], v[168:169], 0, v[60:61]
	v_pk_mul_f32 v[60:61], v[80:81], v[108:109] op_sel_hi:[1,0]
	v_pk_mul_f32 v[58:59], v[58:59], v[108:109] op_sel_hi:[1,0]
	v_pk_mul_f32 v[54:55], v[54:55], v[108:109] op_sel_hi:[1,0]
	v_pk_mul_f32 v[56:57], v[56:57], v[108:109] op_sel_hi:[1,0]
	v_pk_mul_f32 v[96:97], v[108:109], v[106:107] op_sel_hi:[0,1]
	v_pk_mul_f32 v[98:99], v[108:109], v[104:105] op_sel_hi:[0,1]
	v_pk_mul_f32 v[88:89], v[108:109], v[88:89] op_sel_hi:[0,1]
	v_pk_mul_f32 v[100:101], v[108:109], v[102:103] op_sel_hi:[0,1]
	v_mov_b64_e32 v[94:95], s[2:3]
	v_mad_u64_u32 v[94:95], s[2:3], v109, s21, v[94:95]
	v_mad_i32_i24 v95, v63, s21, v95
	v_lshl_add_u64 v[94:95], v[94:95], 0, v[0:1]
	s_waitcnt vmcnt(1)
	v_pk_mul_f32 v[60:61], v[66:67], v[60:61]
	v_pk_mul_f32 v[58:59], v[68:69], v[58:59]
	s_waitcnt vmcnt(0)
	v_pk_mul_f32 v[66:67], v[76:77], v[54:55]
	v_pk_mul_f32 v[68:69], v[78:79], v[56:57]
	v_cvt_pk_bf16_f32 v54, v60, v61
	v_cvt_pk_bf16_f32 v55, v58, v59
	v_cvt_pk_bf16_f32 v56, v66, v67
	v_cvt_pk_bf16_f32 v57, v68, v69
	v_mov_b32_e32 v232, v54
	v_mov_b32_e32 v233, v55
	v_mov_b32_e32 v234, v56
	v_mov_b32_e32 v235, v57
	v_mov_b32_e32 v237, v82
	global_load_dwordx4 v[54:57], v[170:171], off offset:256
	s_nop 0
	global_load_dwordx4 v[58:61], v[84:85], off
	global_load_dwordx4 v[66:69], v[84:85], off offset:16
	global_load_dwordx4 v[76:79], v[170:171], off offset:272
	global_load_dwordx4 v[80:83], v[84:85], off offset:32
	s_nop 0
	global_load_dwordx4 v[84:87], v[84:85], off offset:48
	s_waitcnt vmcnt(5)
	v_pk_mul_f32 v[54:55], v[96:97], v[54:55]
	s_waitcnt vmcnt(4)
	v_mov_b32_e32 v96, v58
	v_mov_b32_e32 v97, v60
	v_mov_b32_e32 v60, v59
	v_pk_mul_f32 v[56:57], v[98:99], v[56:57]
	s_waitcnt vmcnt(3)
	v_mov_b32_e32 v58, v66
	v_mov_b32_e32 v59, v68
	v_mov_b32_e32 v68, v67
	s_waitcnt vmcnt(2)
	v_pk_mul_f32 v[66:67], v[88:89], v[76:77] op_sel:[1,0] op_sel_hi:[0,1]
	v_pk_mul_f32 v[78:79], v[100:101], v[78:79] op_sel:[1,0] op_sel_hi:[0,1]
	s_waitcnt vmcnt(1)
	v_mov_b32_e32 v76, v80
	v_mov_b32_e32 v77, v82
	v_mov_b32_e32 v82, v81
	ds_bpermute_b32 v80, v75, v54
	ds_bpermute_b32 v81, v75, v55
	ds_bpermute_b32 v98, v75, v56
	ds_bpermute_b32 v99, v75, v57
	ds_bpermute_b32 v100, v75, v66
	ds_bpermute_b32 v101, v75, v67
	ds_bpermute_b32 v102, v75, v78
	ds_bpermute_b32 v103, v75, v79
	s_waitcnt vmcnt(0)
	buffer_store_dwordx4 v[228:231], v236, s[56:59], 0 offen sc1
	buffer_store_dwordx4 v[232:235], v237, s[56:59], 0 offen sc1
	v_mov_b32_e32 v89, v86
	v_mov_b32_e32 v86, v85
	s_waitcnt lgkmcnt(6)
	v_pk_mul_f32 v[60:61], v[60:61], v[80:81]
	s_waitcnt lgkmcnt(4)
	v_pk_mul_f32 v[68:69], v[68:69], v[98:99]
	s_waitcnt lgkmcnt(2)
	v_pk_mul_f32 v[80:81], v[82:83], v[100:101]
	s_waitcnt lgkmcnt(0)
	v_pk_mul_f32 v[82:83], v[86:87], v[102:103]
	v_mov_b32_e32 v88, v84
	v_cndmask_b32_e64 v61, v61, -v61, s[40:41]
	v_cndmask_b32_e64 v60, v60, -v60, s[40:41]
	v_cndmask_b32_e64 v69, v69, -v69, s[40:41]
	v_cndmask_b32_e64 v68, v68, -v68, s[40:41]
	v_cndmask_b32_e64 v85, v81, -v81, s[40:41]
	v_cndmask_b32_e64 v84, v80, -v80, s[40:41]
	v_cndmask_b32_e64 v83, v83, -v83, s[40:41]
	v_cndmask_b32_e64 v82, v82, -v82, s[40:41]
	v_pk_fma_f32 v[80:81], v[54:55], v[96:97], v[60:61]
	v_pk_fma_f32 v[58:59], v[56:57], v[58:59], v[68:69]
	v_pk_fma_f32 v[54:55], v[66:67], v[76:77], v[84:85]
	v_pk_fma_f32 v[56:57], v[78:79], v[88:89], v[82:83]
	v_lshl_add_u64 v[84:85], v[94:95], 0, s[80:81]

;     __device__ __forceinline__ void operator()(const f32x4 (&acc)[2][2][4][2], const pg8::Unit& u, int wr, int wc, int fr, int fq) const {
;     ...
;                 float v[2][8];
; #pragma unroll
;                 for (int bj = 0; bj < 2; ++bj)
; #pragma unroll
;                     for (int n = 0; n < 2; ++n)
; #pragma unroll
;                         for (int i = 0; i < 4; ++i) v[bj][4 * n + i] = acc[ai][bj][m][n][i] * rkv;
;                 if (pn < 2) {
.LBB0_155:
	v_pk_mul_f32 v[42:43], v[38:39], v[56:57] op_sel_hi:[1,0]
	v_pk_mul_f32 v[38:39], v[40:41], v[56:57] op_sel_hi:[1,0]
	v_pk_mul_f32 v[34:35], v[34:35], v[56:57] op_sel_hi:[1,0]
	s_andn2_b64 vcc, exec, s[2:3]
	v_pk_mul_f32 v[36:37], v[36:37], v[56:57] op_sel_hi:[1,0]
	s_cbranch_vccnz .LBB0_157
; #define wt16(p, v) wt16b(WSB, (p), (v))
; __device__ __forceinline__ u32x4 pack8(const float (&f)[8]) { u32x4 v; v.x = cvt_pk_bf16(f[0], f[1]); v.y = cvt_pk_bf16(f[2], f[3]); v.z = cvt_pk_bf16(f[4], f[5]); v.w = cvt_pk_bf16(f[6], f[7]); return v; }
;     __device__ __forceinline__ void operator()(const f32x4 (&acc)[2][2][4][2], const pg8::Unit& u, int wr, int wc, int fr, int fq) const {
;     ...
;                 if (pn < 2) {
;                     const int head = 4 * pn + wc;
;                     float ssn = 0.f;
; #pragma unroll
;                     for (int bj = 0; bj < 2; ++bj)
; #pragma unroll
;                         for (int e = 0; e < 8; ++e) ssn += v[bj][e] * v[bj][e];
;                     float pe[8]; unpack8(*(const u32x4*)(U + (size_t)row * NU + UPE + 8 * fq), pe);
; #pragma unroll
;                     for (int e = 0; e < 8; ++e) ssn += pe[e] * pe[e];
;                     ssn += __shfl_xor(ssn, 16); ssn += __shfl_xor(ssn, 32);
;                     const float rk = rsqrtf(ssn * (1.f / 96.f) + EPS);
;                     bf16_t* kb = Kf + ((size_t)(b * 8 + head) * SEQ + s) * 96;
; #pragma unroll
;                     for (int bj = 0; bj < 2; ++bj) {
;                         float o[8];
; #pragma unroll
;                         for (int e = 0; e < 8; ++e) o[e] = v[bj][e] * rk * khn[32 * bj + 8 * fq + e];
;                         wt16(kb + 32 * bj + 8 * fq, pack8(o));
;                     }
;                     float o[8];
; #pragma unroll
;                     for (int e = 0; e < 8; ++e) {
;                         const float mine = pe[e] * rk * khn[64 + 8 * fq + e];
;                         const float other = __shfl_xor(mine, 32);
;                         const float2 c = cs[(size_t)row * 16 + ((8 * fq + e) & 15)];
;                         o[e] = (fq < 2) ? (mine * c.x - other * c.y) : (other * c.y + mine * c.x);
;                     }
;                     wt16(kb + 64 + 8 * fq, pack8(o));
	v_mov_b64_e32 v[40:41], s[70:71]
	v_mad_i64_i32 v[40:41], s[2:3], v184, s85, v[40:41]
	v_lshl_add_u64 v[40:41], v[40:41], 0, v[0:1]
	v_add_co_u32_e32 v40, vcc, 0x1000, v40
	v_pk_mul_f32 v[80:81], v[48:49], v[48:49]
	s_nop 0
	v_addc_co_u32_e32 v41, vcc, 0, v41, vcc
	global_load_dwordx4 v[58:61], v[40:41], off offset:1792
	global_load_dwordx4 v[66:69], v[170:171], off
	global_load_dwordx4 v[76:79], v[170:171], off offset:16
	v_pk_mul_f32 v[40:41], v[46:47], v[46:47]
	v_pk_mul_f32 v[82:83], v[54:55], v[54:55]
	v_add_f32_e32 v40, v40, v41
	v_add_f32_e32 v40, v80, v40
	v_add_f32_e32 v40, v81, v40
	v_add_f32_e32 v40, v82, v40
	v_pk_mul_f32 v[84:85], v[44:45], v[44:45]
	v_add_f32_e32 v40, v83, v40
	v_add_f32_e32 v40, v84, v40
	v_pk_mul_f32 v[86:87], v[42:43], v[42:43]
	v_add_f32_e32 v40, v85, v40
	v_add_f32_e32 v40, v86, v40
	v_pk_mul_f32 v[88:89], v[38:39], v[38:39]
	v_add_f32_e32 v40, v87, v40
	v_add_f32_e32 v40, v88, v40
	v_pk_mul_f32 v[90:91], v[34:35], v[34:35]
	v_add_f32_e32 v40, v89, v40
	v_add_f32_e32 v40, v90, v40
	v_pk_mul_f32 v[92:93], v[36:37], v[36:37]
	v_add_f32_e32 v40, v91, v40
	v_add_f32_e32 v40, v92, v40
	v_and_b32_e32 v75, 64, v247
	v_add_f32_e32 v90, v93, v40
	v_xor_b32_e32 v56, 16, v247
	v_add_u32_e32 v75, 64, v75
	v_cmp_lt_i32_e32 vcc, v56, v75
	s_movk_i32 s21, 0xc0
	s_mov_b32 s58, s62
	v_cndmask_b32_e32 v41, v247, v56, vcc
	v_lshlrev_b32_e32 v56, 2, v41
	s_mov_b32 s59, s63
	v_readlane_b32 s2, v253, 32
	v_readlane_b32 s3, v253, 33
	s_waitcnt vmcnt(0)
	v_lshlrev_b32_e32 v86, 16, v58
	v_and_b32_e32 v87, 0xffff0000, v58
	v_pk_mul_f32 v[88:89], v[86:87], v[86:87]
	v_lshlrev_b32_e32 v84, 16, v59
	v_and_b32_e32 v85, 0xffff0000, v59
	v_add_f32_e32 v88, v90, v88
	v_and_b32_e32 v80, 0xffff0000, v60
	v_lshlrev_b32_e32 v81, 16, v60
	v_and_b32_e32 v82, 0xffff0000, v61
	v_lshlrev_b32_e32 v83, 16, v61
	v_pk_mul_f32 v[60:61], v[84:85], v[84:85]
	v_add_f32_e32 v88, v89, v88
	v_add_f32_e32 v60, v60, v88
	v_pk_mul_f32 v[40:41], v[80:81], v[80:81]
	v_add_f32_e32 v60, v61, v60
	v_add_f32_e32 v41, v41, v60
	v_pk_mul_f32 v[58:59], v[82:83], v[82:83]
	v_add_f32_e32 v40, v40, v41
	v_add_f32_e32 v40, v59, v40
	v_add_f32_e32 v40, v58, v40
	ds_bpermute_b32 v41, v56, v40
	v_xor_b32_e32 v56, 32, v247
	v_cmp_lt_i32_e32 vcc, v56, v75
	v_or_b32_e32 v89, v62, v57
	v_mul_lo_u32 v60, v89, s21
	v_cndmask_b32_e32 v56, v247, v56, vcc
	v_lshlrev_b32_e32 v75, 2, v56
	s_waitcnt lgkmcnt(0)
	v_add_f32_e32 v40, v40, v41
	ds_bpermute_b32 v41, v75, v40
	v_add_u32_e32 v56, v60, v172
	s_waitcnt lgkmcnt(0)
	v_add_f32_e32 v40, v40, v41
	v_fmamk_f32 v40, v40, 0x3c2aaaab, v245
	v_mul_f32_e32 v41, 0x4b800000, v40
	v_cmp_gt_f32_e32 vcc, s83, v40
	s_nop 1
	v_cndmask_b32_e32 v40, v40, v41, vcc
	v_rsq_f32_e32 v40, v40
	s_nop 0
	v_mul_f32_e32 v41, 0x45800000, v40
	v_cndmask_b32_e32 v88, v40, v41, vcc
	v_pk_mul_f32 v[40:41], v[46:47], v[88:89] op_sel_hi:[1,0]
	v_pk_mul_f32 v[46:47], v[48:49], v[88:89] op_sel_hi:[1,0]
	v_pk_mul_f32 v[48:49], v[54:55], v[88:89] op_sel_hi:[1,0]
	v_pk_mul_f32 v[44:45], v[44:45], v[88:89] op_sel_hi:[1,0]
	v_pk_mul_f32 v[40:41], v[66:67], v[40:41]
	v_pk_mul_f32 v[46:47], v[68:69], v[46:47]
	v_pk_mul_f32 v[48:49], v[76:77], v[48:49]
	v_pk_mul_f32 v[54:55], v[78:79], v[44:45]
	v_cvt_pk_bf16_f32 v44, v40, v41
	v_cvt_pk_bf16_f32 v45, v46, v47
	v_cvt_pk_bf16_f32 v46, v48, v49
	v_cvt_pk_bf16_f32 v47, v54, v55
	v_mov_b32_e32 v228, v44
	v_mov_b32_e32 v229, v45
	v_mov_b32_e32 v230, v46
	v_mov_b32_e32 v231, v47
	v_mov_b32_e32 v236, v56
	global_load_dwordx4 v[44:47], v[170:171], off offset:128
	s_nop 0
	global_load_dwordx4 v[54:57], v[170:171], off offset:144
	v_lshlrev_b64 v[40:41], 7, v[184:185]
	v_lshl_add_u64 v[58:59], v[168:169], 0, v[40:41]
	v_pk_mul_f32 v[40:41], v[42:43], v[88:89] op_sel_hi:[1,0]
	v_pk_mul_f32 v[38:39], v[38:39], v[88:89] op_sel_hi:[1,0]
	v_pk_mul_f32 v[34:35], v[34:35], v[88:89] op_sel_hi:[1,0]
	v_pk_mul_f32 v[36:37], v[36:37], v[88:89] op_sel_hi:[1,0]
	v_add_u32_e32 v48, v174, v60
	v_pk_mul_f32 v[68:69], v[88:89], v[86:87] op_sel_hi:[0,1]
	v_pk_mul_f32 v[76:77], v[88:89], v[84:85] op_sel_hi:[0,1]
	v_pk_mul_f32 v[78:79], v[88:89], v[80:81] op_sel_hi:[0,1]
	v_pk_mul_f32 v[80:81], v[88:89], v[82:83] op_sel_hi:[0,1]
	v_mov_b64_e32 v[66:67], s[2:3]
	v_mad_u64_u32 v[66:67], s[2:3], v89, s21, v[66:67]
	v_mad_i32_i24 v67, v63, s21, v67
	v_lshl_add_u64 v[66:67], v[66:67], 0, v[0:1]
	s_waitcnt vmcnt(1)
	v_pk_mul_f32 v[40:41], v[44:45], v[40:41]
	v_pk_mul_f32 v[38:39], v[46:47], v[38:39]
	s_waitcnt vmcnt(0)
	v_pk_mul_f32 v[42:43], v[54:55], v[34:35]
	v_pk_mul_f32 v[44:45], v[56:57], v[36:37]
	v_cvt_pk_bf16_f32 v34, v40, v41
	v_cvt_pk_bf16_f32 v35, v38, v39
	v_cvt_pk_bf16_f32 v36, v42, v43
	v_cvt_pk_bf16_f32 v37, v44, v45
	v_mov_b32_e32 v232, v34
	v_mov_b32_e32 v233, v35
	v_mov_b32_e32 v234, v36
	v_mov_b32_e32 v235, v37
	v_mov_b32_e32 v237, v48
	global_load_dwordx4 v[34:37], v[170:171], off offset:256
	s_nop 0
	global_load_dwordx4 v[38:41], v[58:59], off
	global_load_dwordx4 v[42:45], v[58:59], off offset:16
	global_load_dwordx4 v[46:49], v[170:171], off offset:272
	global_load_dwordx4 v[54:57], v[58:59], off offset:32
	s_nop 0
	global_load_dwordx4 v[58:61], v[58:59], off offset:48
	s_waitcnt vmcnt(5)
	v_pk_mul_f32 v[34:35], v[68:69], v[34:35]
	v_pk_mul_f32 v[36:37], v[76:77], v[36:37]
	s_waitcnt vmcnt(4)
	v_mov_b32_e32 v68, v38
	s_waitcnt vmcnt(2)
	v_pk_mul_f32 v[46:47], v[78:79], v[46:47] op_sel:[1,0] op_sel_hi:[0,1]
	v_pk_mul_f32 v[48:49], v[80:81], v[48:49] op_sel:[1,0] op_sel_hi:[0,1]
	v_mov_b32_e32 v69, v40
	v_mov_b32_e32 v40, v39
	v_mov_b32_e32 v38, v42
	v_mov_b32_e32 v39, v44
	v_mov_b32_e32 v44, v43
	ds_bpermute_b32 v42, v75, v34
	ds_bpermute_b32 v43, v75, v35
	ds_bpermute_b32 v78, v75, v36
	ds_bpermute_b32 v79, v75, v37
	ds_bpermute_b32 v80, v75, v46
	ds_bpermute_b32 v81, v75, v47
	ds_bpermute_b32 v82, v75, v48
	ds_bpermute_b32 v83, v75, v49
	s_waitcnt vmcnt(1)
	v_mov_b32_e32 v77, v56
	v_mov_b32_e32 v56, v55
	s_waitcnt vmcnt(0)
	buffer_store_dwordx4 v[228:231], v236, s[56:59], 0 offen sc1
	buffer_store_dwordx4 v[232:235], v237, s[56:59], 0 offen sc1
	v_mov_b32_e32 v55, v60
	v_mov_b32_e32 v60, v59
	s_waitcnt lgkmcnt(6)
	v_pk_mul_f32 v[40:41], v[40:41], v[42:43]
	s_waitcnt lgkmcnt(4)
	v_pk_mul_f32 v[42:43], v[44:45], v[78:79]
	s_waitcnt lgkmcnt(2)
	v_pk_mul_f32 v[44:45], v[56:57], v[80:81]
	s_waitcnt lgkmcnt(0)
	v_pk_mul_f32 v[56:57], v[60:61], v[82:83]
	v_mov_b32_e32 v76, v54
	v_mov_b32_e32 v54, v58
	v_cndmask_b32_e64 v41, v41, -v41, s[40:41]
	v_cndmask_b32_e64 v40, v40, -v40, s[40:41]
	v_cndmask_b32_e64 v59, v43, -v43, s[40:41]
	v_cndmask_b32_e64 v58, v42, -v42, s[40:41]
	v_cndmask_b32_e64 v45, v45, -v45, s[40:41]
	v_cndmask_b32_e64 v44, v44, -v44, s[40:41]
	v_cndmask_b32_e64 v57, v57, -v57, s[40:41]
	v_cndmask_b32_e64 v56, v56, -v56, s[40:41]
	v_pk_fma_f32 v[42:43], v[34:35], v[68:69], v[40:41]
	v_pk_fma_f32 v[38:39], v[36:37], v[38:39], v[58:59]
	v_pk_fma_f32 v[34:35], v[46:47], v[76:77], v[44:45]
	v_pk_fma_f32 v[36:37], v[48:49], v[54:55], v[56:57]
	v_lshl_add_u64 v[58:59], v[66:67], 0, s[80:81]

;     __device__ __forceinline__ void operator()(const f32x4 (&acc)[2][2][4][2], const pg8::Unit& u, int wr, int wc, int fr, int fq) const {
;     ...
;                 float v[2][8];
; #pragma unroll
;                 for (int bj = 0; bj < 2; ++bj)
; #pragma unroll
;                     for (int n = 0; n < 2; ++n)
; #pragma unroll
;                         for (int i = 0; i < 4; ++i) v[bj][4 * n + i] = acc[ai][bj][m][n][i] * rkv;
;                 if (pn < 2) {
.LBB0_159:
	v_pk_mul_f32 v[26:27], v[22:23], v[36:37] op_sel_hi:[1,0]
	v_pk_mul_f32 v[22:23], v[24:25], v[36:37] op_sel_hi:[1,0]
	v_pk_mul_f32 v[18:19], v[18:19], v[36:37] op_sel_hi:[1,0]
	s_andn2_b64 vcc, exec, s[2:3]
	v_pk_mul_f32 v[20:21], v[20:21], v[36:37] op_sel_hi:[1,0]
	s_cbranch_vccnz .LBB0_161
; #define wt16(p, v) wt16b(WSB, (p), (v))
; __device__ __forceinline__ u32x4 pack8(const float (&f)[8]) { u32x4 v; v.x = cvt_pk_bf16(f[0], f[1]); v.y = cvt_pk_bf16(f[2], f[3]); v.z = cvt_pk_bf16(f[4], f[5]); v.w = cvt_pk_bf16(f[6], f[7]); return v; }
;     __device__ __forceinline__ void operator()(const f32x4 (&acc)[2][2][4][2], const pg8::Unit& u, int wr, int wc, int fr, int fq) const {
;     ...
;                 if (pn < 2) {
;                     const int head = 4 * pn + wc;
;                     float ssn = 0.f;
; #pragma unroll
;                     for (int bj = 0; bj < 2; ++bj)
; #pragma unroll
;                         for (int e = 0; e < 8; ++e) ssn += v[bj][e] * v[bj][e];
;                     float pe[8]; unpack8(*(const u32x4*)(U + (size_t)row * NU + UPE + 8 * fq), pe);
; #pragma unroll
;                     for (int e = 0; e < 8; ++e) ssn += pe[e] * pe[e];
;                     ssn += __shfl_xor(ssn, 16); ssn += __shfl_xor(ssn, 32);
;                     const float rk = rsqrtf(ssn * (1.f / 96.f) + EPS);
;                     bf16_t* kb = Kf + ((size_t)(b * 8 + head) * SEQ + s) * 96;
; #pragma unroll
;                     for (int bj = 0; bj < 2; ++bj) {
;                         float o[8];
; #pragma unroll
;                         for (int e = 0; e < 8; ++e) o[e] = v[bj][e] * rk * khn[32 * bj + 8 * fq + e];
;                         wt16(kb + 32 * bj + 8 * fq, pack8(o));
;                     }
;                     float o[8];
; #pragma unroll
;                     for (int e = 0; e < 8; ++e) {
;                         const float mine = pe[e] * rk * khn[64 + 8 * fq + e];
;                         const float other = __shfl_xor(mine, 32);
;                         const float2 c = cs[(size_t)row * 16 + ((8 * fq + e) & 15)];
;                         o[e] = (fq < 2) ? (mine * c.x - other * c.y) : (other * c.y + mine * c.x);
;                     }
;                     wt16(kb + 64 + 8 * fq, pack8(o));
	v_mov_b64_e32 v[24:25], s[70:71]
	v_mad_i64_i32 v[24:25], s[2:3], v182, s85, v[24:25]
	v_lshl_add_u64 v[24:25], v[24:25], 0, v[0:1]
	v_add_co_u32_e32 v24, vcc, 0x1000, v24
	v_pk_mul_f32 v[54:55], v[32:33], v[32:33]
	s_nop 0
	v_addc_co_u32_e32 v25, vcc, 0, v25, vcc
	global_load_dwordx4 v[38:41], v[24:25], off offset:1792
	global_load_dwordx4 v[42:45], v[170:171], off
	global_load_dwordx4 v[46:49], v[170:171], off offset:16
	v_pk_mul_f32 v[24:25], v[30:31], v[30:31]
	v_pk_mul_f32 v[56:57], v[34:35], v[34:35]
	v_add_f32_e32 v24, v24, v25
	v_add_f32_e32 v24, v54, v24
	v_add_f32_e32 v24, v55, v24
	v_add_f32_e32 v24, v56, v24
	v_pk_mul_f32 v[58:59], v[28:29], v[28:29]
	v_add_f32_e32 v24, v57, v24
	v_add_f32_e32 v24, v58, v24
	v_pk_mul_f32 v[60:61], v[26:27], v[26:27]
	v_add_f32_e32 v24, v59, v24
	v_add_f32_e32 v24, v60, v24
	v_pk_mul_f32 v[66:67], v[22:23], v[22:23]
	v_add_f32_e32 v24, v61, v24
	v_add_f32_e32 v24, v66, v24
	v_pk_mul_f32 v[68:69], v[18:19], v[18:19]
	v_add_f32_e32 v24, v67, v24
	v_add_f32_e32 v24, v68, v24
	v_pk_mul_f32 v[70:71], v[20:21], v[20:21]
	v_add_f32_e32 v24, v69, v24
	v_add_f32_e32 v24, v70, v24
	v_and_b32_e32 v72, 64, v247
	v_add_f32_e32 v68, v71, v24
	v_xor_b32_e32 v36, 16, v247
	v_add_u32_e32 v72, 64, v72
	v_cmp_lt_i32_e32 vcc, v36, v72
	s_movk_i32 s21, 0xc0
	s_mov_b32 s58, s62
	v_cndmask_b32_e32 v25, v247, v36, vcc
	v_lshlrev_b32_e32 v36, 2, v25
	s_mov_b32 s59, s63
	v_readlane_b32 s2, v253, 32
	v_readlane_b32 s3, v253, 33
	s_waitcnt vmcnt(0)
	v_lshlrev_b32_e32 v60, 16, v38
	v_and_b32_e32 v61, 0xffff0000, v38
	v_pk_mul_f32 v[66:67], v[60:61], v[60:61]
	v_lshlrev_b32_e32 v58, 16, v39
	v_and_b32_e32 v59, 0xffff0000, v39
	v_add_f32_e32 v66, v68, v66
	v_and_b32_e32 v54, 0xffff0000, v40
	v_lshlrev_b32_e32 v55, 16, v40
	v_and_b32_e32 v56, 0xffff0000, v41
	v_lshlrev_b32_e32 v57, 16, v41
	v_pk_mul_f32 v[40:41], v[58:59], v[58:59]
	v_add_f32_e32 v66, v67, v66
	v_add_f32_e32 v40, v40, v66
	v_pk_mul_f32 v[24:25], v[54:55], v[54:55]
	v_add_f32_e32 v40, v41, v40
	v_add_f32_e32 v25, v25, v40
	v_pk_mul_f32 v[38:39], v[56:57], v[56:57]
	v_add_f32_e32 v24, v24, v25
	v_add_f32_e32 v24, v39, v24
	v_add_f32_e32 v24, v38, v24
	ds_bpermute_b32 v25, v36, v24
	v_xor_b32_e32 v36, 32, v247
	v_cmp_lt_i32_e32 vcc, v36, v72
	v_or_b32_e32 v68, v62, v37
	s_waitcnt lgkmcnt(0)
	v_add_f32_e32 v24, v24, v25
	v_cndmask_b32_e32 v36, v247, v36, vcc
	v_lshlrev_b32_e32 v67, 2, v36
	ds_bpermute_b32 v25, v67, v24
	v_mul_lo_u32 v36, v68, s21
	v_add_u32_e32 v37, v36, v172
	v_add_u32_e32 v36, v174, v36
	s_waitcnt lgkmcnt(0)
	v_add_f32_e32 v24, v24, v25
	v_fmamk_f32 v24, v24, 0x3c2aaaab, v245
	v_mul_f32_e32 v25, 0x4b800000, v24
	v_cmp_gt_f32_e32 vcc, s83, v24
	s_nop 1
	v_cndmask_b32_e32 v24, v24, v25, vcc
	v_rsq_f32_e32 v24, v24
	s_nop 0
	v_mul_f32_e32 v25, 0x45800000, v24
	v_cndmask_b32_e32 v66, v24, v25, vcc
	v_pk_mul_f32 v[24:25], v[30:31], v[66:67] op_sel_hi:[1,0]
	v_pk_mul_f32 v[30:31], v[32:33], v[66:67] op_sel_hi:[1,0]
	v_pk_mul_f32 v[32:33], v[34:35], v[66:67] op_sel_hi:[1,0]
	v_pk_mul_f32 v[28:29], v[28:29], v[66:67] op_sel_hi:[1,0]
	v_pk_mul_f32 v[24:25], v[42:43], v[24:25]
	v_pk_mul_f32 v[30:31], v[44:45], v[30:31]
	v_pk_mul_f32 v[32:33], v[46:47], v[32:33]
	v_pk_mul_f32 v[34:35], v[48:49], v[28:29]
	v_cvt_pk_bf16_f32 v28, v24, v25
	v_cvt_pk_bf16_f32 v29, v30, v31
	v_cvt_pk_bf16_f32 v30, v32, v33
	v_cvt_pk_bf16_f32 v31, v34, v35
	v_mov_b32_e32 v228, v28
	v_mov_b32_e32 v229, v29
	v_mov_b32_e32 v230, v30
	v_mov_b32_e32 v231, v31
	v_mov_b32_e32 v236, v37
	global_load_dwordx4 v[28:31], v[170:171], off offset:128
	s_nop 0
	global_load_dwordx4 v[32:35], v[170:171], off offset:144
	v_lshlrev_b64 v[24:25], 7, v[182:183]
	v_lshl_add_u64 v[38:39], v[168:169], 0, v[24:25]
	v_pk_mul_f32 v[24:25], v[26:27], v[66:67] op_sel_hi:[1,0]
	v_pk_mul_f32 v[22:23], v[22:23], v[66:67] op_sel_hi:[1,0]
	v_pk_mul_f32 v[18:19], v[18:19], v[66:67] op_sel_hi:[1,0]
	v_pk_mul_f32 v[20:21], v[20:21], v[66:67] op_sel_hi:[1,0]
	v_pk_mul_f32 v[44:45], v[66:67], v[60:61] op_sel_hi:[0,1]
	v_pk_mul_f32 v[46:47], v[66:67], v[58:59] op_sel_hi:[0,1]
	v_pk_mul_f32 v[48:49], v[66:67], v[54:55] op_sel_hi:[0,1]
	v_pk_mul_f32 v[54:55], v[66:67], v[56:57] op_sel_hi:[0,1]
	v_mov_b64_e32 v[42:43], s[2:3]
	v_mad_u64_u32 v[42:43], s[2:3], v68, s21, v[42:43]
	v_mad_i32_i24 v43, v63, s21, v43
	v_lshl_add_u64 v[42:43], v[42:43], 0, v[0:1]
	s_waitcnt vmcnt(1)
	v_pk_mul_f32 v[24:25], v[28:29], v[24:25]
	v_pk_mul_f32 v[22:23], v[30:31], v[22:23]
	s_waitcnt vmcnt(0)
	v_pk_mul_f32 v[26:27], v[32:33], v[18:19]
	v_pk_mul_f32 v[28:29], v[34:35], v[20:21]
	v_cvt_pk_bf16_f32 v18, v24, v25
	v_cvt_pk_bf16_f32 v19, v22, v23
	v_cvt_pk_bf16_f32 v20, v26, v27
	v_cvt_pk_bf16_f32 v21, v28, v29
	v_mov_b32_e32 v232, v18
	v_mov_b32_e32 v233, v19
	v_mov_b32_e32 v234, v20
	v_mov_b32_e32 v235, v21
	v_mov_b32_e32 v237, v36
	global_load_dwordx4 v[18:21], v[170:171], off offset:256
	s_nop 0
	global_load_dwordx4 v[22:25], v[38:39], off
	global_load_dwordx4 v[26:29], v[38:39], off offset:16
	global_load_dwordx4 v[30:33], v[170:171], off offset:272
	global_load_dwordx4 v[34:37], v[38:39], off offset:32
	s_nop 0
	global_load_dwordx4 v[38:41], v[38:39], off offset:48
	s_waitcnt vmcnt(5)
	v_pk_mul_f32 v[18:19], v[44:45], v[18:19]
	v_pk_mul_f32 v[20:21], v[46:47], v[20:21]
	s_waitcnt vmcnt(4)
	v_mov_b32_e32 v44, v22
	s_waitcnt vmcnt(2)
	v_pk_mul_f32 v[30:31], v[48:49], v[30:31] op_sel:[1,0] op_sel_hi:[0,1]
	v_pk_mul_f32 v[32:33], v[54:55], v[32:33] op_sel:[1,0] op_sel_hi:[0,1]
	v_mov_b32_e32 v45, v24
	v_mov_b32_e32 v24, v23
	v_mov_b32_e32 v22, v26
	v_mov_b32_e32 v23, v28
	v_mov_b32_e32 v28, v27
	ds_bpermute_b32 v26, v67, v18
	ds_bpermute_b32 v27, v67, v19
	ds_bpermute_b32 v48, v67, v20
	ds_bpermute_b32 v49, v67, v21
	ds_bpermute_b32 v54, v67, v30
	ds_bpermute_b32 v55, v67, v31
	ds_bpermute_b32 v56, v67, v32
	ds_bpermute_b32 v57, v67, v33
	s_waitcnt vmcnt(1)
	v_mov_b32_e32 v47, v36
	v_mov_b32_e32 v36, v35
	s_waitcnt vmcnt(0)
	buffer_store_dwordx4 v[228:231], v236, s[56:59], 0 offen sc1
	buffer_store_dwordx4 v[232:235], v237, s[56:59], 0 offen sc1
	v_mov_b32_e32 v35, v40
	v_mov_b32_e32 v40, v39
	s_waitcnt lgkmcnt(6)
	v_pk_mul_f32 v[24:25], v[24:25], v[26:27]
	s_waitcnt lgkmcnt(4)
	v_pk_mul_f32 v[26:27], v[28:29], v[48:49]
	s_waitcnt lgkmcnt(2)
	v_pk_mul_f32 v[28:29], v[36:37], v[54:55]
	s_waitcnt lgkmcnt(0)
	v_pk_mul_f32 v[36:37], v[40:41], v[56:57]
	v_mov_b32_e32 v46, v34
	v_mov_b32_e32 v34, v38
	v_cndmask_b32_e64 v25, v25, -v25, s[40:41]
	v_cndmask_b32_e64 v24, v24, -v24, s[40:41]
	v_cndmask_b32_e64 v39, v27, -v27, s[40:41]
	v_cndmask_b32_e64 v38, v26, -v26, s[40:41]
	v_cndmask_b32_e64 v29, v29, -v29, s[40:41]
	v_cndmask_b32_e64 v28, v28, -v28, s[40:41]
	v_cndmask_b32_e64 v37, v37, -v37, s[40:41]
	v_cndmask_b32_e64 v36, v36, -v36, s[40:41]
	v_pk_fma_f32 v[26:27], v[18:19], v[44:45], v[24:25]
	v_pk_fma_f32 v[22:23], v[20:21], v[22:23], v[38:39]
	v_pk_fma_f32 v[18:19], v[30:31], v[46:47], v[28:29]
	v_pk_fma_f32 v[20:21], v[32:33], v[34:35], v[36:37]
	v_lshl_add_u64 v[38:39], v[42:43], 0, s[80:81]

;     __device__ __forceinline__ void operator()(const f32x4 (&acc)[2][2][4][2], const pg8::Unit& u, int wr, int wc, int fr, int fq) const {
;     ...
;                 float v[2][8];
; #pragma unroll
;                 for (int bj = 0; bj < 2; ++bj)
; #pragma unroll
;                     for (int n = 0; n < 2; ++n)
; #pragma unroll
;                         for (int i = 0; i < 4; ++i) v[bj][4 * n + i] = acc[ai][bj][m][n][i] * rkv;
;                 if (pn < 2) {
.LBB0_163:
	v_pk_mul_f32 v[10:11], v[6:7], v[20:21] op_sel_hi:[1,0]
	v_pk_mul_f32 v[6:7], v[8:9], v[20:21] op_sel_hi:[1,0]
	v_pk_mul_f32 v[2:3], v[2:3], v[20:21] op_sel_hi:[1,0]
	s_andn2_b64 vcc, exec, s[2:3]
	v_pk_mul_f32 v[4:5], v[4:5], v[20:21] op_sel_hi:[1,0]
	s_cbranch_vccnz .LBB0_121
; #define wt16(p, v) wt16b(WSB, (p), (v))
; __device__ __forceinline__ u32x4 pack8(const float (&f)[8]) { u32x4 v; v.x = cvt_pk_bf16(f[0], f[1]); v.y = cvt_pk_bf16(f[2], f[3]); v.z = cvt_pk_bf16(f[4], f[5]); v.w = cvt_pk_bf16(f[6], f[7]); return v; }
;     __device__ __forceinline__ void operator()(const f32x4 (&acc)[2][2][4][2], const pg8::Unit& u, int wr, int wc, int fr, int fq) const {
;     ...
;                 if (pn < 2) {
;                     const int head = 4 * pn + wc;
;                     float ssn = 0.f;
; #pragma unroll
;                     for (int bj = 0; bj < 2; ++bj)
; #pragma unroll
;                         for (int e = 0; e < 8; ++e) ssn += v[bj][e] * v[bj][e];
;                     float pe[8]; unpack8(*(const u32x4*)(U + (size_t)row * NU + UPE + 8 * fq), pe);
; #pragma unroll
;                     for (int e = 0; e < 8; ++e) ssn += pe[e] * pe[e];
;                     ssn += __shfl_xor(ssn, 16); ssn += __shfl_xor(ssn, 32);
;                     const float rk = rsqrtf(ssn * (1.f / 96.f) + EPS);
;                     bf16_t* kb = Kf + ((size_t)(b * 8 + head) * SEQ + s) * 96;
; #pragma unroll
;                     for (int bj = 0; bj < 2; ++bj) {
;                         float o[8];
; #pragma unroll
;                         for (int e = 0; e < 8; ++e) o[e] = v[bj][e] * rk * khn[32 * bj + 8 * fq + e];
;                         wt16(kb + 32 * bj + 8 * fq, pack8(o));
;                     }
;                     float o[8];
; #pragma unroll
;                     for (int e = 0; e < 8; ++e) {
;                         const float mine = pe[e] * rk * khn[64 + 8 * fq + e];
;                         const float other = __shfl_xor(mine, 32);
;                         const float2 c = cs[(size_t)row * 16 + ((8 * fq + e) & 15)];
;                         o[e] = (fq < 2) ? (mine * c.x - other * c.y) : (other * c.y + mine * c.x);
;                     }
;                     wt16(kb + 64 + 8 * fq, pack8(o));
	v_mov_b64_e32 v[8:9], s[70:71]
	v_mad_i64_i32 v[8:9], s[2:3], v180, s85, v[8:9]
	v_lshl_add_u64 v[8:9], v[8:9], 0, v[0:1]
	v_add_co_u32_e32 v8, vcc, 0x1000, v8
	v_pk_mul_f32 v[34:35], v[16:17], v[16:17]
	s_nop 0
	v_addc_co_u32_e32 v9, vcc, 0, v9, vcc
	global_load_dwordx4 v[22:25], v[8:9], off offset:1792
	global_load_dwordx4 v[26:29], v[170:171], off
	global_load_dwordx4 v[30:33], v[170:171], off offset:16
	v_pk_mul_f32 v[8:9], v[14:15], v[14:15]
	v_pk_mul_f32 v[36:37], v[18:19], v[18:19]
	v_add_f32_e32 v8, v8, v9
	v_add_f32_e32 v8, v34, v8
	v_add_f32_e32 v8, v35, v8
	v_add_f32_e32 v8, v36, v8
	v_pk_mul_f32 v[38:39], v[12:13], v[12:13]
	v_add_f32_e32 v8, v37, v8
	v_add_f32_e32 v8, v38, v8
	v_pk_mul_f32 v[40:41], v[10:11], v[10:11]
	v_add_f32_e32 v8, v39, v8
	v_add_f32_e32 v8, v40, v8
	v_pk_mul_f32 v[42:43], v[6:7], v[6:7]
	v_add_f32_e32 v8, v41, v8
	v_add_f32_e32 v8, v42, v8
	v_pk_mul_f32 v[44:45], v[2:3], v[2:3]
	v_add_f32_e32 v8, v43, v8
	v_add_f32_e32 v8, v44, v8
	v_pk_mul_f32 v[46:47], v[4:5], v[4:5]
	v_add_f32_e32 v8, v45, v8
	v_add_f32_e32 v8, v46, v8
	v_and_b32_e32 v48, 64, v247
	v_add_f32_e32 v44, v47, v8
	v_xor_b32_e32 v20, 16, v247
	v_add_u32_e32 v48, 64, v48
	v_cmp_lt_i32_e32 vcc, v20, v48
	s_movk_i32 s21, 0xc0
	s_mov_b32 s58, s62
	v_cndmask_b32_e32 v9, v247, v20, vcc
	v_lshlrev_b32_e32 v20, 2, v9
	s_mov_b32 s59, s63
	v_readlane_b32 s2, v253, 32
	v_readlane_b32 s3, v253, 33
	s_waitcnt vmcnt(0)
	v_lshlrev_b32_e32 v40, 16, v22
	v_and_b32_e32 v41, 0xffff0000, v22
	v_pk_mul_f32 v[42:43], v[40:41], v[40:41]
	v_lshlrev_b32_e32 v38, 16, v23
	v_and_b32_e32 v39, 0xffff0000, v23
	v_add_f32_e32 v42, v44, v42
	v_and_b32_e32 v34, 0xffff0000, v24
	v_lshlrev_b32_e32 v35, 16, v24
	v_and_b32_e32 v36, 0xffff0000, v25
	v_lshlrev_b32_e32 v37, 16, v25
	v_pk_mul_f32 v[24:25], v[38:39], v[38:39]
	v_add_f32_e32 v42, v43, v42
	v_add_f32_e32 v24, v24, v42
	v_pk_mul_f32 v[8:9], v[34:35], v[34:35]
	v_add_f32_e32 v24, v25, v24
	v_add_f32_e32 v9, v9, v24
	v_pk_mul_f32 v[22:23], v[36:37], v[36:37]
	v_add_f32_e32 v8, v8, v9
	v_add_f32_e32 v8, v23, v8
	v_add_f32_e32 v8, v22, v8
	ds_bpermute_b32 v9, v20, v8
	v_xor_b32_e32 v20, 32, v247
	v_cmp_lt_i32_e32 vcc, v20, v48
	v_or_b32_e32 v44, v62, v21
	s_waitcnt lgkmcnt(0)
	v_add_f32_e32 v8, v8, v9
	v_cndmask_b32_e32 v20, v247, v20, vcc
	v_lshlrev_b32_e32 v43, 2, v20
	ds_bpermute_b32 v9, v43, v8
	v_mul_lo_u32 v20, v44, s21
	v_add_u32_e32 v21, v20, v172
	v_add_u32_e32 v20, v174, v20
	s_waitcnt lgkmcnt(0)
	v_add_f32_e32 v8, v8, v9
	v_fmamk_f32 v8, v8, 0x3c2aaaab, v245
	v_mul_f32_e32 v9, 0x4b800000, v8
	v_cmp_gt_f32_e32 vcc, s83, v8
	s_nop 1
	v_cndmask_b32_e32 v8, v8, v9, vcc
	v_rsq_f32_e32 v8, v8
	s_nop 0
	v_mul_f32_e32 v9, 0x45800000, v8
	v_cndmask_b32_e32 v42, v8, v9, vcc
	v_pk_mul_f32 v[8:9], v[14:15], v[42:43] op_sel_hi:[1,0]
	v_pk_mul_f32 v[14:15], v[16:17], v[42:43] op_sel_hi:[1,0]
	v_pk_mul_f32 v[16:17], v[18:19], v[42:43] op_sel_hi:[1,0]
	v_pk_mul_f32 v[12:13], v[12:13], v[42:43] op_sel_hi:[1,0]
	v_pk_mul_f32 v[8:9], v[26:27], v[8:9]
	v_pk_mul_f32 v[14:15], v[28:29], v[14:15]
	v_pk_mul_f32 v[16:17], v[30:31], v[16:17]
	v_pk_mul_f32 v[18:19], v[32:33], v[12:13]
	v_cvt_pk_bf16_f32 v12, v8, v9
	v_cvt_pk_bf16_f32 v13, v14, v15
	v_cvt_pk_bf16_f32 v14, v16, v17
	v_cvt_pk_bf16_f32 v15, v18, v19
	v_mov_b32_e32 v228, v12
	v_mov_b32_e32 v229, v13
	v_mov_b32_e32 v230, v14
	v_mov_b32_e32 v231, v15
	v_mov_b32_e32 v236, v21
	global_load_dwordx4 v[12:15], v[170:171], off offset:128
	s_nop 0
	global_load_dwordx4 v[16:19], v[170:171], off offset:144
	v_lshlrev_b64 v[8:9], 7, v[180:181]
	v_lshl_add_u64 v[22:23], v[168:169], 0, v[8:9]
	v_pk_mul_f32 v[8:9], v[10:11], v[42:43] op_sel_hi:[1,0]
	v_pk_mul_f32 v[6:7], v[6:7], v[42:43] op_sel_hi:[1,0]
	v_pk_mul_f32 v[2:3], v[2:3], v[42:43] op_sel_hi:[1,0]
	v_pk_mul_f32 v[4:5], v[4:5], v[42:43] op_sel_hi:[1,0]
	v_pk_mul_f32 v[28:29], v[42:43], v[40:41] op_sel_hi:[0,1]
	v_pk_mul_f32 v[30:31], v[42:43], v[38:39] op_sel_hi:[0,1]
	v_pk_mul_f32 v[32:33], v[42:43], v[34:35] op_sel_hi:[0,1]
	v_pk_mul_f32 v[34:35], v[42:43], v[36:37] op_sel_hi:[0,1]
	v_mov_b64_e32 v[26:27], s[2:3]
	v_mad_u64_u32 v[26:27], s[2:3], v44, s21, v[26:27]
	v_mad_i32_i24 v27, v63, s21, v27
	v_lshl_add_u64 v[26:27], v[26:27], 0, v[0:1]
	s_waitcnt vmcnt(1)
	v_pk_mul_f32 v[8:9], v[12:13], v[8:9]
	v_pk_mul_f32 v[6:7], v[14:15], v[6:7]
	s_waitcnt vmcnt(0)
	v_pk_mul_f32 v[10:11], v[16:17], v[2:3]
	v_pk_mul_f32 v[12:13], v[18:19], v[4:5]
	v_cvt_pk_bf16_f32 v2, v8, v9
	v_cvt_pk_bf16_f32 v3, v6, v7
	v_cvt_pk_bf16_f32 v4, v10, v11
	v_cvt_pk_bf16_f32 v5, v12, v13
	v_mov_b32_e32 v232, v2
	v_mov_b32_e32 v233, v3
	v_mov_b32_e32 v234, v4
	v_mov_b32_e32 v235, v5
	v_mov_b32_e32 v237, v20
	global_load_dwordx4 v[2:5], v[170:171], off offset:256
	s_nop 0
	global_load_dwordx4 v[6:9], v[22:23], off
	global_load_dwordx4 v[10:13], v[22:23], off offset:16
	global_load_dwordx4 v[14:17], v[170:171], off offset:272
	global_load_dwordx4 v[18:21], v[22:23], off offset:32
	s_nop 0
	global_load_dwordx4 v[22:25], v[22:23], off offset:48
	s_waitcnt vmcnt(5)
	v_pk_mul_f32 v[2:3], v[28:29], v[2:3]
	v_pk_mul_f32 v[4:5], v[30:31], v[4:5]
	s_waitcnt vmcnt(4)
	v_mov_b32_e32 v28, v6
	s_waitcnt vmcnt(2)
	v_pk_mul_f32 v[14:15], v[32:33], v[14:15] op_sel:[1,0] op_sel_hi:[0,1]
	v_pk_mul_f32 v[16:17], v[34:35], v[16:17] op_sel:[1,0] op_sel_hi:[0,1]
	v_mov_b32_e32 v29, v8
	v_mov_b32_e32 v8, v7
	v_mov_b32_e32 v6, v10
	v_mov_b32_e32 v7, v12
	v_mov_b32_e32 v12, v11
	ds_bpermute_b32 v10, v43, v2
	ds_bpermute_b32 v11, v43, v3
	ds_bpermute_b32 v32, v43, v4
	ds_bpermute_b32 v33, v43, v5
	ds_bpermute_b32 v34, v43, v14
	ds_bpermute_b32 v35, v43, v15
	ds_bpermute_b32 v36, v43, v16
	ds_bpermute_b32 v37, v43, v17
	s_waitcnt vmcnt(1)
	v_mov_b32_e32 v31, v20
	v_mov_b32_e32 v20, v19
	s_waitcnt vmcnt(0)
	buffer_store_dwordx4 v[228:231], v236, s[56:59], 0 offen sc1
	buffer_store_dwordx4 v[232:235], v237, s[56:59], 0 offen sc1
	v_mov_b32_e32 v19, v24
	v_mov_b32_e32 v24, v23
	s_waitcnt lgkmcnt(6)
	v_pk_mul_f32 v[8:9], v[8:9], v[10:11]
	s_waitcnt lgkmcnt(4)
	v_pk_mul_f32 v[10:11], v[12:13], v[32:33]
	s_waitcnt lgkmcnt(2)
	v_pk_mul_f32 v[12:13], v[20:21], v[34:35]
	s_waitcnt lgkmcnt(0)
	v_pk_mul_f32 v[20:21], v[24:25], v[36:37]
	v_mov_b32_e32 v30, v18
	v_mov_b32_e32 v18, v22
	v_cndmask_b32_e64 v9, v9, -v9, s[40:41]
	v_cndmask_b32_e64 v8, v8, -v8, s[40:41]
	v_cndmask_b32_e64 v23, v11, -v11, s[40:41]
	v_cndmask_b32_e64 v22, v10, -v10, s[40:41]
	v_cndmask_b32_e64 v13, v13, -v13, s[40:41]
	v_cndmask_b32_e64 v12, v12, -v12, s[40:41]
	v_cndmask_b32_e64 v21, v21, -v21, s[40:41]
	v_cndmask_b32_e64 v20, v20, -v20, s[40:41]
	v_pk_fma_f32 v[10:11], v[2:3], v[28:29], v[8:9]
	v_pk_fma_f32 v[6:7], v[4:5], v[6:7], v[22:23]
	v_pk_fma_f32 v[2:3], v[14:15], v[30:31], v[12:13]
	v_pk_fma_f32 v[4:5], v[16:17], v[18:19], v[20:21]
	v_lshl_add_u64 v[22:23], v[26:27], 0, s[80:81]
	s_branch .LBB0_121
